# P1: after the K-loop, touch the next tile's first two K-tiles of both operands (one dword per line) so the next header hits L2
# baseline (speedup 1.0000x reference)
;     ...
;   const int srow = tid >> 3, skc = tid & 7;
;   const u16* Ag = A + (size_t)(m0 + srow) * K + skc * 8;
;   const u16* Bg[4];
; #pragma unroll
;   for (int i = 0; i < 4; ++i) { int n = n0 + srow + 64 * i; n = n < nmax ? n : nmax - 1; Bg[i] = Bt + (size_t)n * K + skc * 8; }
;   const int nk = nk_override ? nk_override : K / 64;
; #pragma unroll
;   for (int i = 0; i < 4; ++i) { ra[i] = *(const u32x4*)(Ag + (size_t)(64 * i) * K); rb[i] = *(const u32x4*)(Bg[i]); }
; #pragma unroll
;   for (int i = 0; i < 4; ++i) { *(u32x4*)(As0 + (srow + 64 * i) * LD + skc * 8) = ra[i]; *(u32x4*)(Bs0 + (srow + 64 * i) * LD + skc * 8) = rb[i]; }
;   if (nk > 1) {
; #pragma unroll
;     for (int i = 0; i < 4; ++i) { ra[i] = *(const u32x4*)(Ag + (size_t)(64 * i) * K + 64); rb[i] = *(const u32x4*)(Bg[i] + 64); }
;   }
;   for (int kt = 0; kt < nk; ++kt) {
;     __syncthreads();
;     if (kt + 1 < nk) {
;       u16* aw = As0 + ((kt + 1) & 1) * 256 * LD;
;       u16* bw = Bs0 + ((kt + 1) & 1) * 256 * LD;
; #pragma unroll
;       for (int i = 0; i < 4; ++i) { *(u32x4*)(aw + (srow + 64 * i) * LD + skc * 8) = ra[i]; *(u32x4*)(bw + (srow + 64 * i) * LD + skc * 8) = rb[i]; }
;     }
;     if (kt + 2 < nk) {
; #pragma unroll
;       for (int i = 0; i < 4; ++i) { ra[i] = *(const u32x4*)(Ag + (size_t)(64 * i) * K + (kt + 2) * 64); rb[i] = *(const u32x4*)(Bg[i] + (kt + 2) * 64); }
;     }
.LBB0_107:
	s_lshl_b32 s34, s34, 1
	s_add_i32 s34, s34, s40
	s_and_b32 s30, s35, 1
	s_or_b32 s30, s34, s30
	s_lshl_b32 s59, s62, 8
	v_ashrrev_i32_e32 v42, 3, v227
	s_lshl_b32 s35, s30, 8
	s_waitcnt vmcnt(3)
	v_add_u32_e32 v10, s59, v42
	s_waitcnt vmcnt(0)
	v_add_u32_e32 v4, s35, v42
	v_lshlrev_b32_e32 v2, 4, v227
	v_min_i32_e32 v8, 0x107f, v10
	v_ashrrev_i32_e32 v5, 31, v4
	v_and_b32_e32 v2, 0x70, v2
	v_ashrrev_i32_e32 v9, 31, v8
	v_lshlrev_b64 v[4:5], 11, v[4:5]
	s_waitcnt lgkmcnt(0)
	v_lshl_add_u64 v[6:7], s[18:19], 0, v[2:3]
	v_lshlrev_b64 v[8:9], 11, v[8:9]
	v_lshl_add_u64 v[228:229], v[6:7], 0, v[8:9]
	v_min_i32_e32 v8, 0x103f, v10
	v_lshl_add_u64 v[4:5], s[16:17], 0, v[4:5]
	v_ashrrev_i32_e32 v9, 31, v8
	v_lshl_add_u64 v[230:231], v[4:5], 0, v[2:3]
	v_lshlrev_b64 v[8:9], 11, v[8:9]
	v_add_co_u32_e32 v232, vcc, s42, v230
	v_lshl_add_u64 v[36:37], v[6:7], 0, v[8:9]
	v_min_i32_e32 v8, 0xfff, v10
	v_addc_co_u32_e32 v233, vcc, 0, v231, vcc
	v_ashrrev_i32_e32 v9, 31, v8
	v_add_co_u32_e32 v16, vcc, s42, v36
	v_lshlrev_b64 v[8:9], 11, v[8:9]
	s_nop 0
	v_addc_co_u32_e32 v17, vcc, 0, v37, vcc
	v_lshl_add_u64 v[38:39], v[6:7], 0, v[8:9]
	v_min_i32_e32 v8, 0xfbf, v10
	v_add_co_u32_e32 v68, vcc, s43, v230
	v_ashrrev_i32_e32 v9, 31, v8
	s_nop 0
	v_addc_co_u32_e32 v69, vcc, 0, v231, vcc
	v_lshlrev_b64 v[8:9], 11, v[8:9]
	v_add_co_u32_e32 v24, vcc, s43, v38
	v_lshl_add_u64 v[40:41], v[6:7], 0, v[8:9]
	global_load_dwordx4 v[4:7], v[230:231], off
	global_load_dwordx4 v[8:11], v[228:229], off
	v_addc_co_u32_e32 v25, vcc, 0, v39, vcc
	global_load_dwordx4 v[16:19], v[16:17], off
	v_add_co_u32_e32 v28, vcc, s44, v40
	global_load_dwordx4 v[24:27], v[24:25], off
	s_nop 0
	v_addc_co_u32_e32 v29, vcc, 0, v41, vcc
	global_load_dwordx4 v[28:31], v[28:29], off
	v_add_co_u32_e32 v70, vcc, s44, v230
	global_load_dwordx4 v[12:15], v[232:233], off
	global_load_dwordx4 v[20:23], v[68:69], off
	v_addc_co_u32_e32 v71, vcc, 0, v231, vcc
	global_load_dwordx4 v[32:35], v[70:71], off
	v_mul_lo_u32 v42, v42, s46
	v_add3_u32 v251, s45, v2, v42
	v_add3_u32 v250, 0, v2, v42
	v_lshl_add_u64 v[238:239], v[36:37], 0, s[24:25]
	v_lshl_add_u64 v[234:235], v[38:39], 0, s[26:27]
	v_lshl_add_u64 v[236:237], v[40:41], 0, s[28:29]
	global_load_dwordx4 v[36:39], v[228:229], off offset:128
	global_load_dwordx4 v[40:43], v[238:239], off offset:128
	global_load_dwordx4 v[44:47], v[234:235], off offset:128
	global_load_dwordx4 v[48:51], v[236:237], off offset:128
	global_load_dwordx4 v[52:55], v[230:231], off offset:128
	global_load_dwordx4 v[56:59], v[232:233], off offset:128
	global_load_dwordx4 v[60:63], v[68:69], off offset:128
	global_load_dwordx4 v[64:67], v[70:71], off offset:128
	s_ashr_i32 s36, s60, 6
	s_bfe_u32 s37, s36, 0x10001
	s_ashr_i32 s38, s60, 8
	s_and_b64 s[30:31], s[6:7], exec
	s_cselect_b32 s37, s37, s38
	s_xor_b64 s[6:7], s[6:7], -1
	s_cmp_lt_i32 s36, 4
	v_and_b32_e32 v225, 31, v227
	s_cselect_b64 s[30:31], -1, 0
	s_lshl_b32 s36, s37, 7
	v_bfe_u32 v247, v227, 5, 1
	v_or_b32_e32 v2, s36, v225
	v_mul_lo_u32 v2, v2, s46
	v_lshlrev_b32_e32 v226, 4, v247
	s_lshl_b32 s61, s20, 6
	v_add3_u32 v248, 0, v2, v226
	v_or_b32_e32 v2, s61, v225
	v_mul_lo_u32 v2, v2, s46
	s_or_b64 s[30:31], s[6:7], s[30:31]
	v_add3_u32 v249, s45, v2, v226
	s_waitcnt vmcnt(14)
	ds_write_b128 v251, v[8:11]
	s_waitcnt vmcnt(13)
	ds_write_b128 v251, v[16:19] offset:9216
	s_waitcnt vmcnt(12)
	ds_write_b128 v251, v[24:27] offset:18432
	s_waitcnt vmcnt(11)
	ds_write_b128 v251, v[28:31] offset:27648
	ds_write_b128 v250, v[4:7]
	s_waitcnt vmcnt(10)
	ds_write_b128 v250, v[12:15] offset:9216
	s_waitcnt vmcnt(9)
	ds_write_b128 v250, v[20:23] offset:18432
	s_waitcnt vmcnt(8)
	ds_write_b128 v250, v[32:35] offset:27648
	s_waitcnt lgkmcnt(0)
	s_barrier
	s_andn2_b64 vcc, exec, s[30:31]
	s_cbranch_vccnz .Lp1_stage_only
	v_lshrrev_b32_e32 v227, 3, v223
	v_lshlrev_b32_e32 v227, 11, v227
	v_lshlrev_b32_e32 v2, 4, v223
	v_and_b32_e32 v2, 0x70, v2
	v_or_b32_e32 v227, v227, v2
	s_lshl_b32 s6, s35, 11
	s_add_u32 s74, s16, s6
	s_addc_u32 s75, s17, 0
	s_add_u32 s76, s74, 0x20000
	s_addc_u32 s77, s75, 0
	s_add_u32 s78, s74, 0x40000
	s_addc_u32 s79, s75, 0
	s_add_u32 s80, s74, 0x60000
	s_addc_u32 s81, s75, 0
	s_lshl_b32 s6, s59, 11
	s_add_u32 s82, s18, s6
	s_addc_u32 s83, s19, 0
	s_add_u32 s84, s82, 0x20000
	s_addc_u32 s85, s83, 0
	s_add_u32 s86, s82, 0x40000
	s_addc_u32 s87, s83, 0
	s_add_u32 s92, s82, 0x60000
	s_addc_u32 s93, s83, 0
	global_load_dwordx4 v[146:149], v227, s[74:75] offset:256
	global_load_dwordx4 v[178:181], v227, s[82:83] offset:256
	global_load_dwordx4 v[150:153], v227, s[76:77] offset:256
	global_load_dwordx4 v[182:185], v227, s[84:85] offset:256
	global_load_dwordx4 v[154:157], v227, s[78:79] offset:256
	global_load_dwordx4 v[186:189], v227, s[86:87] offset:256
	global_load_dwordx4 v[158:161], v227, s[80:81] offset:256
	global_load_dwordx4 v[190:193], v227, s[92:93] offset:256
	global_load_dwordx4 v[162:165], v227, s[74:75] offset:384
	global_load_dwordx4 v[194:197], v227, s[82:83] offset:384
	global_load_dwordx4 v[166:169], v227, s[76:77] offset:384
	global_load_dwordx4 v[198:201], v227, s[84:85] offset:384
	global_load_dwordx4 v[170:173], v227, s[78:79] offset:384
	global_load_dwordx4 v[202:205], v227, s[86:87] offset:384
	global_load_dwordx4 v[174:177], v227, s[80:81] offset:384
	global_load_dwordx4 v[206:209], v227, s[92:93] offset:384
	s_waitcnt vmcnt(23)
	ds_write_b128 v251, v[36:39] offset:36864
	s_waitcnt vmcnt(22)
	ds_write_b128 v251, v[40:43] offset:46080
	s_waitcnt vmcnt(21)
	ds_write_b128 v251, v[44:47] offset:55296
	s_waitcnt vmcnt(20)
	ds_write_b128 v251, v[48:51] offset:64512
	s_waitcnt vmcnt(19)
;     ...
;   for (int kt = 0; kt < nk; ++kt) {
;     __syncthreads();
;     if (kt + 1 < nk) {
;       u16* aw = As0 + ((kt + 1) & 1) * 256 * LD;
;       u16* bw = Bs0 + ((kt + 1) & 1) * 256 * LD;
; #pragma unroll
;       for (int i = 0; i < 4; ++i) { *(u32x4*)(aw + (srow + 64 * i) * LD + skc * 8) = ra[i]; *(u32x4*)(bw + (srow + 64 * i) * LD + skc * 8) = rb[i]; }
;     }
;     if (kt + 2 < nk) {
; #pragma unroll
;       for (int i = 0; i < 4; ++i) { ra[i] = *(const u32x4*)(Ag + (size_t)(64 * i) * K + (kt + 2) * 64); rb[i] = *(const u32x4*)(Bg[i] + (kt + 2) * 64); }
;     }
;     __builtin_amdgcn_sched_barrier(0);
;     const u16* as = As0 + (kt & 1) * 256 * LD + (wr * 128 + l31) * LD + h * 8;
;     const u16* bs = Bs0 + (kt & 1) * 256 * LD + (wc * 64 + l31) * LD + h * 8;
;     if (domma)
; #pragma unroll
;     for (int ks = 0; ks < 4; ++ks) {
;       bf16x8 wf[2], xf[4];
; #pragma unroll
;       for (int ct = 0; ct < 2; ++ct) wf[ct] = *(const bf16x8*)(bs + ct * 32 * LD + ks * 16);
; #pragma unroll
;       for (int tt = 0; tt < 4; ++tt) xf[tt] = *(const bf16x8*)(as + tt * 32 * LD + ks * 16);
; #pragma unroll
;       for (int ct = 0; ct < 2; ++ct)
; #pragma unroll
;         for (int tt = 0; tt < 4; ++tt) acc[ct][tt] = __builtin_amdgcn_mfma_f32_32x32x16_bf16(wf[ct], xf[tt], acc[ct][tt], 0, 0, 0);
;     }
	ds_write_b128 v250, v[52:55] offset:36864
	s_waitcnt vmcnt(18)
	ds_write_b128 v250, v[56:59] offset:46080
	s_waitcnt vmcnt(17)
	ds_write_b128 v250, v[60:63] offset:55296
	s_waitcnt vmcnt(16)
	ds_write_b128 v250, v[64:67] offset:64512
	ds_read_b128 v[210:213], v249
	ds_read_b128 v[236:239], v248
	ds_read_b128 v[214:217], v249 offset:4608
	ds_read_b128 v[2:5], v248 offset:4608
	ds_read_b128 v[6:9], v248 offset:9216
	ds_read_b128 v[10:13], v248 offset:13824
	s_waitcnt lgkmcnt(4)
	v_mfma_f32_32x32x16_bf16 v[114:129], v[210:213], v[236:239], 0
	ds_read_b128 v[228:231], v249 offset:32
	s_waitcnt lgkmcnt(4)
	v_mfma_f32_32x32x16_bf16 v[130:145], v[214:217], v[236:239], 0
	ds_read_b128 v[14:17], v248 offset:32
	s_waitcnt lgkmcnt(4)
	v_mfma_f32_32x32x16_bf16 v[82:97], v[210:213], v[2:5], 0
	ds_read_b128 v[232:235], v249 offset:4640
	v_mfma_f32_32x32x16_bf16 v[98:113], v[214:217], v[2:5], 0
	ds_read_b128 v[236:239], v248 offset:4640
	s_waitcnt lgkmcnt(5)
	v_mfma_f32_32x32x16_bf16 v[50:65], v[210:213], v[6:9], 0
	ds_read_b128 v[2:5], v248 offset:9248
	v_mfma_f32_32x32x16_bf16 v[66:81], v[214:217], v[6:9], 0
	s_waitcnt lgkmcnt(5)
	v_mfma_f32_32x32x16_bf16 v[18:33], v[210:213], v[10:13], 0
	ds_read_b128 v[6:9], v248 offset:13856
	v_mfma_f32_32x32x16_bf16 v[34:49], v[214:217], v[10:13], 0
	s_waitcnt lgkmcnt(4)
	v_mfma_f32_32x32x16_bf16 v[114:129], v[228:231], v[14:17], v[114:129]
	ds_read_b128 v[210:213], v249 offset:64
	s_waitcnt lgkmcnt(4)
	v_mfma_f32_32x32x16_bf16 v[130:145], v[232:235], v[14:17], v[130:145]
	ds_read_b128 v[10:13], v248 offset:64
	s_waitcnt lgkmcnt(4)
	v_mfma_f32_32x32x16_bf16 v[82:97], v[228:231], v[236:239], v[82:97]
	ds_read_b128 v[214:217], v249 offset:4672
	v_mfma_f32_32x32x16_bf16 v[98:113], v[232:235], v[236:239], v[98:113]
	ds_read_b128 v[14:17], v248 offset:4672
	s_waitcnt lgkmcnt(5)
	v_mfma_f32_32x32x16_bf16 v[50:65], v[228:231], v[2:5], v[50:65]
	ds_read_b128 v[236:239], v248 offset:9280
	v_mfma_f32_32x32x16_bf16 v[66:81], v[232:235], v[2:5], v[66:81]
	s_waitcnt lgkmcnt(5)
	v_mfma_f32_32x32x16_bf16 v[18:33], v[228:231], v[6:9], v[18:33]
	ds_read_b128 v[2:5], v248 offset:13888
	v_mfma_f32_32x32x16_bf16 v[34:49], v[232:235], v[6:9], v[34:49]
	s_waitcnt lgkmcnt(4)
	v_mfma_f32_32x32x16_bf16 v[114:129], v[210:213], v[10:13], v[114:129]
	ds_read_b128 v[228:231], v249 offset:96
	s_waitcnt lgkmcnt(4)
	v_mfma_f32_32x32x16_bf16 v[130:145], v[214:217], v[10:13], v[130:145]
	ds_read_b128 v[6:9], v248 offset:96
	s_waitcnt lgkmcnt(4)
	v_mfma_f32_32x32x16_bf16 v[82:97], v[210:213], v[14:17], v[82:97]
	ds_read_b128 v[232:235], v249 offset:4704
	v_mfma_f32_32x32x16_bf16 v[98:113], v[214:217], v[14:17], v[98:113]
	ds_read_b128 v[10:13], v248 offset:4704
	s_waitcnt lgkmcnt(5)
	v_mfma_f32_32x32x16_bf16 v[50:65], v[210:213], v[236:239], v[50:65]
	ds_read_b128 v[14:17], v248 offset:9312
	v_mfma_f32_32x32x16_bf16 v[66:81], v[214:217], v[236:239], v[66:81]
	s_waitcnt lgkmcnt(5)
	v_mfma_f32_32x32x16_bf16 v[18:33], v[210:213], v[2:5], v[18:33]
	ds_read_b128 v[236:239], v248 offset:13920
	v_mfma_f32_32x32x16_bf16 v[34:49], v[214:217], v[2:5], v[34:49]
	s_waitcnt lgkmcnt(4)
	v_mfma_f32_32x32x16_bf16 v[114:129], v[228:231], v[6:9], v[114:129]
	s_waitcnt lgkmcnt(3)
	v_mfma_f32_32x32x16_bf16 v[130:145], v[232:235], v[6:9], v[130:145]
	s_waitcnt lgkmcnt(2)
	v_mfma_f32_32x32x16_bf16 v[82:97], v[228:231], v[10:13], v[82:97]
	v_mfma_f32_32x32x16_bf16 v[98:113], v[232:235], v[10:13], v[98:113]
	s_waitcnt lgkmcnt(1)
	v_mfma_f32_32x32x16_bf16 v[50:65], v[228:231], v[14:17], v[50:65]
	v_mfma_f32_32x32x16_bf16 v[66:81], v[232:235], v[14:17], v[66:81]
	s_waitcnt lgkmcnt(0)
	v_mfma_f32_32x32x16_bf16 v[18:33], v[228:231], v[236:239], v[18:33]
	v_mfma_f32_32x32x16_bf16 v[34:49], v[232:235], v[236:239], v[34:49]
	s_barrier
	ds_read_b128 v[210:213], v249 offset:36864
	ds_read_b128 v[236:239], v248 offset:36864
	ds_read_b128 v[214:217], v249 offset:41472
	ds_read_b128 v[2:5], v248 offset:41472
	ds_read_b128 v[6:9], v248 offset:46080
	ds_read_b128 v[10:13], v248 offset:50688
	s_waitcnt lgkmcnt(4)
	v_mfma_f32_32x32x16_bf16 v[114:129], v[210:213], v[236:239], v[114:129]
	ds_read_b128 v[228:231], v249 offset:36896
	s_waitcnt lgkmcnt(4)
	v_mfma_f32_32x32x16_bf16 v[130:145], v[214:217], v[236:239], v[130:145]
	ds_read_b128 v[14:17], v248 offset:36896
	s_waitcnt lgkmcnt(4)
	v_mfma_f32_32x32x16_bf16 v[82:97], v[210:213], v[2:5], v[82:97]
	ds_read_b128 v[232:235], v249 offset:41504
	v_mfma_f32_32x32x16_bf16 v[98:113], v[214:217], v[2:5], v[98:113]
	ds_read_b128 v[236:239], v248 offset:41504
	s_waitcnt vmcnt(15)
	ds_write_b128 v250, v[146:149]
	s_waitcnt lgkmcnt(6)
	v_mfma_f32_32x32x16_bf16 v[50:65], v[210:213], v[6:9], v[50:65]
	ds_read_b128 v[2:5], v248 offset:46112
	v_mfma_f32_32x32x16_bf16 v[66:81], v[214:217], v[6:9], v[66:81]
	global_load_dwordx4 v[146:149], v227, s[74:75] offset:512
	s_waitcnt lgkmcnt(6)
	v_mfma_f32_32x32x16_bf16 v[18:33], v[210:213], v[10:13], v[18:33]
	ds_read_b128 v[6:9], v248 offset:50720
	s_waitcnt vmcnt(15)
	ds_write_b128 v251, v[178:181]
	v_mfma_f32_32x32x16_bf16 v[34:49], v[214:217], v[10:13], v[34:49]
	s_waitcnt lgkmcnt(6)
	v_mfma_f32_32x32x16_bf16 v[114:129], v[228:231], v[14:17], v[114:129]
	ds_read_b128 v[210:213], v249 offset:36928
	global_load_dwordx4 v[178:181], v227, s[82:83] offset:512
	s_waitcnt lgkmcnt(6)
	v_mfma_f32_32x32x16_bf16 v[130:145], v[232:235], v[14:17], v[130:145]
	ds_read_b128 v[10:13], v248 offset:36928
	s_waitcnt vmcnt(15)
	ds_write_b128 v250, v[150:153] offset:9216
	s_waitcnt lgkmcnt(7)
;     ...
;   for (int kt = 0; kt < nk; ++kt) {
;     __syncthreads();
;     if (kt + 1 < nk) {
;       u16* aw = As0 + ((kt + 1) & 1) * 256 * LD;
;       u16* bw = Bs0 + ((kt + 1) & 1) * 256 * LD;
; #pragma unroll
;       for (int i = 0; i < 4; ++i) { *(u32x4*)(aw + (srow + 64 * i) * LD + skc * 8) = ra[i]; *(u32x4*)(bw + (srow + 64 * i) * LD + skc * 8) = rb[i]; }
;     }
;     if (kt + 2 < nk) {
; #pragma unroll
;       for (int i = 0; i < 4; ++i) { ra[i] = *(const u32x4*)(Ag + (size_t)(64 * i) * K + (kt + 2) * 64); rb[i] = *(const u32x4*)(Bg[i] + (kt + 2) * 64); }
;     }
;     __builtin_amdgcn_sched_barrier(0);
;     const u16* as = As0 + (kt & 1) * 256 * LD + (wr * 128 + l31) * LD + h * 8;
;     const u16* bs = Bs0 + (kt & 1) * 256 * LD + (wc * 64 + l31) * LD + h * 8;
;     if (domma)
; #pragma unroll
;     for (int ks = 0; ks < 4; ++ks) {
;       bf16x8 wf[2], xf[4];
; #pragma unroll
;       for (int ct = 0; ct < 2; ++ct) wf[ct] = *(const bf16x8*)(bs + ct * 32 * LD + ks * 16);
; #pragma unroll
;       for (int tt = 0; tt < 4; ++tt) xf[tt] = *(const bf16x8*)(as + tt * 32 * LD + ks * 16);
; #pragma unroll
;       for (int ct = 0; ct < 2; ++ct)
; #pragma unroll
;         for (int tt = 0; tt < 4; ++tt) acc[ct][tt] = __builtin_amdgcn_mfma_f32_32x32x16_bf16(wf[ct], xf[tt], acc[ct][tt], 0, 0, 0);
;     }
	v_mfma_f32_32x32x16_bf16 v[82:97], v[228:231], v[236:239], v[82:97]
	ds_read_b128 v[214:217], v249 offset:41536
	v_mfma_f32_32x32x16_bf16 v[98:113], v[232:235], v[236:239], v[98:113]
	ds_read_b128 v[14:17], v248 offset:41536
	global_load_dwordx4 v[150:153], v227, s[76:77] offset:512
	s_waitcnt lgkmcnt(7)
	v_mfma_f32_32x32x16_bf16 v[50:65], v[228:231], v[2:5], v[50:65]
	ds_read_b128 v[236:239], v248 offset:46144
	s_waitcnt vmcnt(15)
	ds_write_b128 v251, v[182:185] offset:9216
	v_mfma_f32_32x32x16_bf16 v[66:81], v[232:235], v[2:5], v[66:81]
	s_waitcnt lgkmcnt(8)
	v_mfma_f32_32x32x16_bf16 v[18:33], v[228:231], v[6:9], v[18:33]
	ds_read_b128 v[2:5], v248 offset:50752
	global_load_dwordx4 v[182:185], v227, s[84:85] offset:512
	v_mfma_f32_32x32x16_bf16 v[34:49], v[232:235], v[6:9], v[34:49]
	s_waitcnt vmcnt(15)
	ds_write_b128 v250, v[154:157] offset:18432
	s_waitcnt lgkmcnt(7)
	v_mfma_f32_32x32x16_bf16 v[114:129], v[210:213], v[10:13], v[114:129]
	ds_read_b128 v[228:231], v249 offset:36960
	s_waitcnt lgkmcnt(6)
	v_mfma_f32_32x32x16_bf16 v[130:145], v[214:217], v[10:13], v[130:145]
	ds_read_b128 v[6:9], v248 offset:36960
	global_load_dwordx4 v[154:157], v227, s[78:79] offset:512
	s_waitcnt lgkmcnt(6)
	v_mfma_f32_32x32x16_bf16 v[82:97], v[210:213], v[14:17], v[82:97]
	ds_read_b128 v[232:235], v249 offset:41568
	s_waitcnt vmcnt(15)
	ds_write_b128 v251, v[186:189] offset:18432
	v_mfma_f32_32x32x16_bf16 v[98:113], v[214:217], v[14:17], v[98:113]
	ds_read_b128 v[10:13], v248 offset:41568
	s_waitcnt lgkmcnt(8)
	v_mfma_f32_32x32x16_bf16 v[50:65], v[210:213], v[236:239], v[50:65]
	ds_read_b128 v[14:17], v248 offset:46176
	global_load_dwordx4 v[186:189], v227, s[86:87] offset:512
	v_mfma_f32_32x32x16_bf16 v[66:81], v[214:217], v[236:239], v[66:81]
	s_waitcnt vmcnt(15)
	ds_write_b128 v250, v[158:161] offset:27648
	s_waitcnt lgkmcnt(8)
	v_mfma_f32_32x32x16_bf16 v[18:33], v[210:213], v[2:5], v[18:33]
	ds_read_b128 v[236:239], v248 offset:50784
	v_mfma_f32_32x32x16_bf16 v[34:49], v[214:217], v[2:5], v[34:49]
	global_load_dwordx4 v[158:161], v227, s[80:81] offset:512
	s_waitcnt lgkmcnt(6)
	v_mfma_f32_32x32x16_bf16 v[114:129], v[228:231], v[6:9], v[114:129]
	s_waitcnt vmcnt(15)
	ds_write_b128 v251, v[190:193] offset:27648
	s_waitcnt lgkmcnt(6)
	v_mfma_f32_32x32x16_bf16 v[130:145], v[232:235], v[6:9], v[130:145]
	s_waitcnt lgkmcnt(4)
	v_mfma_f32_32x32x16_bf16 v[82:97], v[228:231], v[10:13], v[82:97]
	global_load_dwordx4 v[190:193], v227, s[92:93] offset:512
	v_mfma_f32_32x32x16_bf16 v[98:113], v[232:235], v[10:13], v[98:113]
	s_waitcnt lgkmcnt(3)
	v_mfma_f32_32x32x16_bf16 v[50:65], v[228:231], v[14:17], v[50:65]
	v_mfma_f32_32x32x16_bf16 v[66:81], v[232:235], v[14:17], v[66:81]
	s_waitcnt lgkmcnt(1)
	v_mfma_f32_32x32x16_bf16 v[18:33], v[228:231], v[236:239], v[18:33]
	v_mfma_f32_32x32x16_bf16 v[34:49], v[232:235], v[236:239], v[34:49]
	s_waitcnt lgkmcnt(0)
	s_barrier
	ds_read_b128 v[210:213], v249
	ds_read_b128 v[236:239], v248
	ds_read_b128 v[214:217], v249 offset:4608
	ds_read_b128 v[2:5], v248 offset:4608
	ds_read_b128 v[6:9], v248 offset:9216
	ds_read_b128 v[10:13], v248 offset:13824
	s_waitcnt lgkmcnt(4)
	v_mfma_f32_32x32x16_bf16 v[114:129], v[210:213], v[236:239], v[114:129]
	ds_read_b128 v[228:231], v249 offset:32
	s_waitcnt lgkmcnt(4)
	v_mfma_f32_32x32x16_bf16 v[130:145], v[214:217], v[236:239], v[130:145]
	ds_read_b128 v[14:17], v248 offset:32
	s_waitcnt lgkmcnt(4)
	v_mfma_f32_32x32x16_bf16 v[82:97], v[210:213], v[2:5], v[82:97]
	ds_read_b128 v[232:235], v249 offset:4640
	v_mfma_f32_32x32x16_bf16 v[98:113], v[214:217], v[2:5], v[98:113]
	ds_read_b128 v[236:239], v248 offset:4640
	s_waitcnt vmcnt(15)
	ds_write_b128 v250, v[162:165] offset:36864
	s_waitcnt lgkmcnt(6)
	v_mfma_f32_32x32x16_bf16 v[50:65], v[210:213], v[6:9], v[50:65]
	ds_read_b128 v[2:5], v248 offset:9248
	v_mfma_f32_32x32x16_bf16 v[66:81], v[214:217], v[6:9], v[66:81]
	global_load_dwordx4 v[162:165], v227, s[74:75] offset:640
	s_waitcnt lgkmcnt(6)
	v_mfma_f32_32x32x16_bf16 v[18:33], v[210:213], v[10:13], v[18:33]
	ds_read_b128 v[6:9], v248 offset:13856
	s_waitcnt vmcnt(15)
	ds_write_b128 v251, v[194:197] offset:36864
	v_mfma_f32_32x32x16_bf16 v[34:49], v[214:217], v[10:13], v[34:49]
	s_waitcnt lgkmcnt(6)
	v_mfma_f32_32x32x16_bf16 v[114:129], v[228:231], v[14:17], v[114:129]
	ds_read_b128 v[210:213], v249 offset:64
	global_load_dwordx4 v[194:197], v227, s[82:83] offset:640
	s_waitcnt lgkmcnt(6)
	v_mfma_f32_32x32x16_bf16 v[130:145], v[232:235], v[14:17], v[130:145]
	ds_read_b128 v[10:13], v248 offset:64
	s_waitcnt vmcnt(15)
	ds_write_b128 v250, v[166:169] offset:46080
	s_waitcnt lgkmcnt(7)
	v_mfma_f32_32x32x16_bf16 v[82:97], v[228:231], v[236:239], v[82:97]
	ds_read_b128 v[214:217], v249 offset:4672
	v_mfma_f32_32x32x16_bf16 v[98:113], v[232:235], v[236:239], v[98:113]
	ds_read_b128 v[14:17], v248 offset:4672
	global_load_dwordx4 v[166:169], v227, s[76:77] offset:640
	s_waitcnt lgkmcnt(7)
	v_mfma_f32_32x32x16_bf16 v[50:65], v[228:231], v[2:5], v[50:65]
	ds_read_b128 v[236:239], v248 offset:9280
	s_waitcnt vmcnt(15)
	ds_write_b128 v251, v[198:201] offset:46080
	v_mfma_f32_32x32x16_bf16 v[66:81], v[232:235], v[2:5], v[66:81]
	s_waitcnt lgkmcnt(8)
	v_mfma_f32_32x32x16_bf16 v[18:33], v[228:231], v[6:9], v[18:33]
	ds_read_b128 v[2:5], v248 offset:13888
	global_load_dwordx4 v[198:201], v227, s[84:85] offset:640
	v_mfma_f32_32x32x16_bf16 v[34:49], v[232:235], v[6:9], v[34:49]
	s_waitcnt vmcnt(15)
	ds_write_b128 v250, v[170:173] offset:55296
	s_waitcnt lgkmcnt(7)
	v_mfma_f32_32x32x16_bf16 v[114:129], v[210:213], v[10:13], v[114:129]
	ds_read_b128 v[228:231], v249 offset:96
	s_waitcnt lgkmcnt(6)
;     ...
;   for (int kt = 0; kt < nk; ++kt) {
;     __syncthreads();
;     if (kt + 1 < nk) {
;       u16* aw = As0 + ((kt + 1) & 1) * 256 * LD;
;       u16* bw = Bs0 + ((kt + 1) & 1) * 256 * LD;
; #pragma unroll
;       for (int i = 0; i < 4; ++i) { *(u32x4*)(aw + (srow + 64 * i) * LD + skc * 8) = ra[i]; *(u32x4*)(bw + (srow + 64 * i) * LD + skc * 8) = rb[i]; }
;     }
;     if (kt + 2 < nk) {
; #pragma unroll
;       for (int i = 0; i < 4; ++i) { ra[i] = *(const u32x4*)(Ag + (size_t)(64 * i) * K + (kt + 2) * 64); rb[i] = *(const u32x4*)(Bg[i] + (kt + 2) * 64); }
;     }
;     __builtin_amdgcn_sched_barrier(0);
;     const u16* as = As0 + (kt & 1) * 256 * LD + (wr * 128 + l31) * LD + h * 8;
;     const u16* bs = Bs0 + (kt & 1) * 256 * LD + (wc * 64 + l31) * LD + h * 8;
;     if (domma)
; #pragma unroll
;     for (int ks = 0; ks < 4; ++ks) {
;       bf16x8 wf[2], xf[4];
; #pragma unroll
;       for (int ct = 0; ct < 2; ++ct) wf[ct] = *(const bf16x8*)(bs + ct * 32 * LD + ks * 16);
; #pragma unroll
;       for (int tt = 0; tt < 4; ++tt) xf[tt] = *(const bf16x8*)(as + tt * 32 * LD + ks * 16);
; #pragma unroll
;       for (int ct = 0; ct < 2; ++ct)
; #pragma unroll
;         for (int tt = 0; tt < 4; ++tt) acc[ct][tt] = __builtin_amdgcn_mfma_f32_32x32x16_bf16(wf[ct], xf[tt], acc[ct][tt], 0, 0, 0);
;     }
	v_mfma_f32_32x32x16_bf16 v[130:145], v[214:217], v[10:13], v[130:145]
	ds_read_b128 v[6:9], v248 offset:96
	global_load_dwordx4 v[170:173], v227, s[78:79] offset:640
	s_waitcnt lgkmcnt(6)
	v_mfma_f32_32x32x16_bf16 v[82:97], v[210:213], v[14:17], v[82:97]
	ds_read_b128 v[232:235], v249 offset:4704
	s_waitcnt vmcnt(15)
	ds_write_b128 v251, v[202:205] offset:55296
	v_mfma_f32_32x32x16_bf16 v[98:113], v[214:217], v[14:17], v[98:113]
	ds_read_b128 v[10:13], v248 offset:4704
	s_waitcnt lgkmcnt(8)
	v_mfma_f32_32x32x16_bf16 v[50:65], v[210:213], v[236:239], v[50:65]
	ds_read_b128 v[14:17], v248 offset:9312
	global_load_dwordx4 v[202:205], v227, s[86:87] offset:640
	v_mfma_f32_32x32x16_bf16 v[66:81], v[214:217], v[236:239], v[66:81]
	s_waitcnt vmcnt(15)
	ds_write_b128 v250, v[174:177] offset:64512
	s_waitcnt lgkmcnt(8)
	v_mfma_f32_32x32x16_bf16 v[18:33], v[210:213], v[2:5], v[18:33]
	ds_read_b128 v[236:239], v248 offset:13920
	v_mfma_f32_32x32x16_bf16 v[34:49], v[214:217], v[2:5], v[34:49]
	global_load_dwordx4 v[174:177], v227, s[80:81] offset:640
	s_waitcnt lgkmcnt(6)
	v_mfma_f32_32x32x16_bf16 v[114:129], v[228:231], v[6:9], v[114:129]
	s_waitcnt vmcnt(15)
	ds_write_b128 v251, v[206:209] offset:64512
	s_waitcnt lgkmcnt(6)
	v_mfma_f32_32x32x16_bf16 v[130:145], v[232:235], v[6:9], v[130:145]
	s_waitcnt lgkmcnt(4)
	v_mfma_f32_32x32x16_bf16 v[82:97], v[228:231], v[10:13], v[82:97]
	global_load_dwordx4 v[206:209], v227, s[92:93] offset:640
	v_mfma_f32_32x32x16_bf16 v[98:113], v[232:235], v[10:13], v[98:113]
	s_waitcnt lgkmcnt(3)
	v_mfma_f32_32x32x16_bf16 v[50:65], v[228:231], v[14:17], v[50:65]
	v_mfma_f32_32x32x16_bf16 v[66:81], v[232:235], v[14:17], v[66:81]
	s_waitcnt lgkmcnt(1)
	v_mfma_f32_32x32x16_bf16 v[18:33], v[228:231], v[236:239], v[18:33]
	v_mfma_f32_32x32x16_bf16 v[34:49], v[232:235], v[236:239], v[34:49]
	s_waitcnt lgkmcnt(0)
	s_barrier
	ds_read_b128 v[210:213], v249 offset:36864
	ds_read_b128 v[236:239], v248 offset:36864
	ds_read_b128 v[214:217], v249 offset:41472
	ds_read_b128 v[2:5], v248 offset:41472
	ds_read_b128 v[6:9], v248 offset:46080
	ds_read_b128 v[10:13], v248 offset:50688
	s_waitcnt lgkmcnt(4)
	v_mfma_f32_32x32x16_bf16 v[114:129], v[210:213], v[236:239], v[114:129]
	ds_read_b128 v[228:231], v249 offset:36896
	s_waitcnt lgkmcnt(4)
	v_mfma_f32_32x32x16_bf16 v[130:145], v[214:217], v[236:239], v[130:145]
	ds_read_b128 v[14:17], v248 offset:36896
	s_waitcnt lgkmcnt(4)
	v_mfma_f32_32x32x16_bf16 v[82:97], v[210:213], v[2:5], v[82:97]
	ds_read_b128 v[232:235], v249 offset:41504
	v_mfma_f32_32x32x16_bf16 v[98:113], v[214:217], v[2:5], v[98:113]
	ds_read_b128 v[236:239], v248 offset:41504
	s_waitcnt vmcnt(15)
	ds_write_b128 v250, v[146:149]
	s_waitcnt lgkmcnt(6)
	v_mfma_f32_32x32x16_bf16 v[50:65], v[210:213], v[6:9], v[50:65]
	ds_read_b128 v[2:5], v248 offset:46112
	v_mfma_f32_32x32x16_bf16 v[66:81], v[214:217], v[6:9], v[66:81]
	global_load_dwordx4 v[146:149], v227, s[74:75] offset:768
	s_waitcnt lgkmcnt(6)
	v_mfma_f32_32x32x16_bf16 v[18:33], v[210:213], v[10:13], v[18:33]
	ds_read_b128 v[6:9], v248 offset:50720
	s_waitcnt vmcnt(15)
	ds_write_b128 v251, v[178:181]
	v_mfma_f32_32x32x16_bf16 v[34:49], v[214:217], v[10:13], v[34:49]
	s_waitcnt lgkmcnt(6)
	v_mfma_f32_32x32x16_bf16 v[114:129], v[228:231], v[14:17], v[114:129]
	ds_read_b128 v[210:213], v249 offset:36928
	global_load_dwordx4 v[178:181], v227, s[82:83] offset:768
	s_waitcnt lgkmcnt(6)
	v_mfma_f32_32x32x16_bf16 v[130:145], v[232:235], v[14:17], v[130:145]
	ds_read_b128 v[10:13], v248 offset:36928
	s_waitcnt vmcnt(15)
	ds_write_b128 v250, v[150:153] offset:9216
	s_waitcnt lgkmcnt(7)
	v_mfma_f32_32x32x16_bf16 v[82:97], v[228:231], v[236:239], v[82:97]
	ds_read_b128 v[214:217], v249 offset:41536
	v_mfma_f32_32x32x16_bf16 v[98:113], v[232:235], v[236:239], v[98:113]
	ds_read_b128 v[14:17], v248 offset:41536
	global_load_dwordx4 v[150:153], v227, s[76:77] offset:768
	s_waitcnt lgkmcnt(7)
	v_mfma_f32_32x32x16_bf16 v[50:65], v[228:231], v[2:5], v[50:65]
	ds_read_b128 v[236:239], v248 offset:46144
	s_waitcnt vmcnt(15)
	ds_write_b128 v251, v[182:185] offset:9216
	v_mfma_f32_32x32x16_bf16 v[66:81], v[232:235], v[2:5], v[66:81]
	s_waitcnt lgkmcnt(8)
	v_mfma_f32_32x32x16_bf16 v[18:33], v[228:231], v[6:9], v[18:33]
	ds_read_b128 v[2:5], v248 offset:50752
	global_load_dwordx4 v[182:185], v227, s[84:85] offset:768
	v_mfma_f32_32x32x16_bf16 v[34:49], v[232:235], v[6:9], v[34:49]
	s_waitcnt vmcnt(15)
	ds_write_b128 v250, v[154:157] offset:18432
	s_waitcnt lgkmcnt(7)
	v_mfma_f32_32x32x16_bf16 v[114:129], v[210:213], v[10:13], v[114:129]
	ds_read_b128 v[228:231], v249 offset:36960
	s_waitcnt lgkmcnt(6)
	v_mfma_f32_32x32x16_bf16 v[130:145], v[214:217], v[10:13], v[130:145]
	ds_read_b128 v[6:9], v248 offset:36960
	global_load_dwordx4 v[154:157], v227, s[78:79] offset:768
	s_waitcnt lgkmcnt(6)
	v_mfma_f32_32x32x16_bf16 v[82:97], v[210:213], v[14:17], v[82:97]
	ds_read_b128 v[232:235], v249 offset:41568
	s_waitcnt vmcnt(15)
	ds_write_b128 v251, v[186:189] offset:18432
	v_mfma_f32_32x32x16_bf16 v[98:113], v[214:217], v[14:17], v[98:113]
	ds_read_b128 v[10:13], v248 offset:41568
	s_waitcnt lgkmcnt(8)
	v_mfma_f32_32x32x16_bf16 v[50:65], v[210:213], v[236:239], v[50:65]
	ds_read_b128 v[14:17], v248 offset:46176
	global_load_dwordx4 v[186:189], v227, s[86:87] offset:768
	v_mfma_f32_32x32x16_bf16 v[66:81], v[214:217], v[236:239], v[66:81]
	s_waitcnt vmcnt(15)
	ds_write_b128 v250, v[158:161] offset:27648
	s_waitcnt lgkmcnt(8)
	v_mfma_f32_32x32x16_bf16 v[18:33], v[210:213], v[2:5], v[18:33]
	ds_read_b128 v[236:239], v248 offset:50784
	v_mfma_f32_32x32x16_bf16 v[34:49], v[214:217], v[2:5], v[34:49]
	global_load_dwordx4 v[158:161], v227, s[80:81] offset:768
	s_waitcnt lgkmcnt(6)
	v_mfma_f32_32x32x16_bf16 v[114:129], v[228:231], v[6:9], v[114:129]
	s_waitcnt vmcnt(15)
	ds_write_b128 v251, v[190:193] offset:27648
	s_waitcnt lgkmcnt(6)
	v_mfma_f32_32x32x16_bf16 v[130:145], v[232:235], v[6:9], v[130:145]
	s_waitcnt lgkmcnt(4)
	v_mfma_f32_32x32x16_bf16 v[82:97], v[228:231], v[10:13], v[82:97]
	global_load_dwordx4 v[190:193], v227, s[92:93] offset:768
	v_mfma_f32_32x32x16_bf16 v[98:113], v[232:235], v[10:13], v[98:113]
	s_waitcnt lgkmcnt(3)
	v_mfma_f32_32x32x16_bf16 v[50:65], v[228:231], v[14:17], v[50:65]
	v_mfma_f32_32x32x16_bf16 v[66:81], v[232:235], v[14:17], v[66:81]
	s_waitcnt lgkmcnt(1)
	v_mfma_f32_32x32x16_bf16 v[18:33], v[228:231], v[236:239], v[18:33]
	v_mfma_f32_32x32x16_bf16 v[34:49], v[232:235], v[236:239], v[34:49]
	s_waitcnt lgkmcnt(0)
	s_barrier
;     ...
;   for (int kt = 0; kt < nk; ++kt) {
;     __syncthreads();
;     if (kt + 1 < nk) {
;       u16* aw = As0 + ((kt + 1) & 1) * 256 * LD;
;       u16* bw = Bs0 + ((kt + 1) & 1) * 256 * LD;
; #pragma unroll
;       for (int i = 0; i < 4; ++i) { *(u32x4*)(aw + (srow + 64 * i) * LD + skc * 8) = ra[i]; *(u32x4*)(bw + (srow + 64 * i) * LD + skc * 8) = rb[i]; }
;     }
;     if (kt + 2 < nk) {
; #pragma unroll
;       for (int i = 0; i < 4; ++i) { ra[i] = *(const u32x4*)(Ag + (size_t)(64 * i) * K + (kt + 2) * 64); rb[i] = *(const u32x4*)(Bg[i] + (kt + 2) * 64); }
;     }
;     __builtin_amdgcn_sched_barrier(0);
;     const u16* as = As0 + (kt & 1) * 256 * LD + (wr * 128 + l31) * LD + h * 8;
;     const u16* bs = Bs0 + (kt & 1) * 256 * LD + (wc * 64 + l31) * LD + h * 8;
;     if (domma)
; #pragma unroll
;     for (int ks = 0; ks < 4; ++ks) {
;       bf16x8 wf[2], xf[4];
; #pragma unroll
;       for (int ct = 0; ct < 2; ++ct) wf[ct] = *(const bf16x8*)(bs + ct * 32 * LD + ks * 16);
; #pragma unroll
;       for (int tt = 0; tt < 4; ++tt) xf[tt] = *(const bf16x8*)(as + tt * 32 * LD + ks * 16);
; #pragma unroll
;       for (int ct = 0; ct < 2; ++ct)
; #pragma unroll
;         for (int tt = 0; tt < 4; ++tt) acc[ct][tt] = __builtin_amdgcn_mfma_f32_32x32x16_bf16(wf[ct], xf[tt], acc[ct][tt], 0, 0, 0);
;     }
	ds_read_b128 v[210:213], v249
	ds_read_b128 v[236:239], v248
	ds_read_b128 v[214:217], v249 offset:4608
	ds_read_b128 v[2:5], v248 offset:4608
	ds_read_b128 v[6:9], v248 offset:9216
	ds_read_b128 v[10:13], v248 offset:13824
	s_waitcnt lgkmcnt(4)
	v_mfma_f32_32x32x16_bf16 v[114:129], v[210:213], v[236:239], v[114:129]
	ds_read_b128 v[228:231], v249 offset:32
	s_waitcnt lgkmcnt(4)
	v_mfma_f32_32x32x16_bf16 v[130:145], v[214:217], v[236:239], v[130:145]
	ds_read_b128 v[14:17], v248 offset:32
	s_waitcnt lgkmcnt(4)
	v_mfma_f32_32x32x16_bf16 v[82:97], v[210:213], v[2:5], v[82:97]
	ds_read_b128 v[232:235], v249 offset:4640
	v_mfma_f32_32x32x16_bf16 v[98:113], v[214:217], v[2:5], v[98:113]
	ds_read_b128 v[236:239], v248 offset:4640
	s_waitcnt vmcnt(15)
	ds_write_b128 v250, v[162:165] offset:36864
	s_waitcnt lgkmcnt(6)
	v_mfma_f32_32x32x16_bf16 v[50:65], v[210:213], v[6:9], v[50:65]
	ds_read_b128 v[2:5], v248 offset:9248
	v_mfma_f32_32x32x16_bf16 v[66:81], v[214:217], v[6:9], v[66:81]
	global_load_dwordx4 v[162:165], v227, s[74:75] offset:896
	s_waitcnt lgkmcnt(6)
	v_mfma_f32_32x32x16_bf16 v[18:33], v[210:213], v[10:13], v[18:33]
	ds_read_b128 v[6:9], v248 offset:13856
	s_waitcnt vmcnt(15)
	ds_write_b128 v251, v[194:197] offset:36864
	v_mfma_f32_32x32x16_bf16 v[34:49], v[214:217], v[10:13], v[34:49]
	s_waitcnt lgkmcnt(6)
	v_mfma_f32_32x32x16_bf16 v[114:129], v[228:231], v[14:17], v[114:129]
	ds_read_b128 v[210:213], v249 offset:64
	global_load_dwordx4 v[194:197], v227, s[82:83] offset:896
	s_waitcnt lgkmcnt(6)
	v_mfma_f32_32x32x16_bf16 v[130:145], v[232:235], v[14:17], v[130:145]
	ds_read_b128 v[10:13], v248 offset:64
	s_waitcnt vmcnt(15)
	ds_write_b128 v250, v[166:169] offset:46080
	s_waitcnt lgkmcnt(7)
	v_mfma_f32_32x32x16_bf16 v[82:97], v[228:231], v[236:239], v[82:97]
	ds_read_b128 v[214:217], v249 offset:4672
	v_mfma_f32_32x32x16_bf16 v[98:113], v[232:235], v[236:239], v[98:113]
	ds_read_b128 v[14:17], v248 offset:4672
	global_load_dwordx4 v[166:169], v227, s[76:77] offset:896
	s_waitcnt lgkmcnt(7)
	v_mfma_f32_32x32x16_bf16 v[50:65], v[228:231], v[2:5], v[50:65]
	ds_read_b128 v[236:239], v248 offset:9280
	s_waitcnt vmcnt(15)
	ds_write_b128 v251, v[198:201] offset:46080
	v_mfma_f32_32x32x16_bf16 v[66:81], v[232:235], v[2:5], v[66:81]
	s_waitcnt lgkmcnt(8)
	v_mfma_f32_32x32x16_bf16 v[18:33], v[228:231], v[6:9], v[18:33]
	ds_read_b128 v[2:5], v248 offset:13888
	global_load_dwordx4 v[198:201], v227, s[84:85] offset:896
	v_mfma_f32_32x32x16_bf16 v[34:49], v[232:235], v[6:9], v[34:49]
	s_waitcnt vmcnt(15)
	ds_write_b128 v250, v[170:173] offset:55296
	s_waitcnt lgkmcnt(7)
	v_mfma_f32_32x32x16_bf16 v[114:129], v[210:213], v[10:13], v[114:129]
	ds_read_b128 v[228:231], v249 offset:96
	s_waitcnt lgkmcnt(6)
	v_mfma_f32_32x32x16_bf16 v[130:145], v[214:217], v[10:13], v[130:145]
	ds_read_b128 v[6:9], v248 offset:96
	global_load_dwordx4 v[170:173], v227, s[78:79] offset:896
	s_waitcnt lgkmcnt(6)
	v_mfma_f32_32x32x16_bf16 v[82:97], v[210:213], v[14:17], v[82:97]
	ds_read_b128 v[232:235], v249 offset:4704
	s_waitcnt vmcnt(15)
	ds_write_b128 v251, v[202:205] offset:55296
	v_mfma_f32_32x32x16_bf16 v[98:113], v[214:217], v[14:17], v[98:113]
	ds_read_b128 v[10:13], v248 offset:4704
	s_waitcnt lgkmcnt(8)
	v_mfma_f32_32x32x16_bf16 v[50:65], v[210:213], v[236:239], v[50:65]
	ds_read_b128 v[14:17], v248 offset:9312
	global_load_dwordx4 v[202:205], v227, s[86:87] offset:896
	v_mfma_f32_32x32x16_bf16 v[66:81], v[214:217], v[236:239], v[66:81]
	s_waitcnt vmcnt(15)
	ds_write_b128 v250, v[174:177] offset:64512
	s_waitcnt lgkmcnt(8)
	v_mfma_f32_32x32x16_bf16 v[18:33], v[210:213], v[2:5], v[18:33]
	ds_read_b128 v[236:239], v248 offset:13920
	v_mfma_f32_32x32x16_bf16 v[34:49], v[214:217], v[2:5], v[34:49]
	global_load_dwordx4 v[174:177], v227, s[80:81] offset:896
	s_waitcnt lgkmcnt(6)
	v_mfma_f32_32x32x16_bf16 v[114:129], v[228:231], v[6:9], v[114:129]
	s_waitcnt vmcnt(15)
	ds_write_b128 v251, v[206:209] offset:64512
	s_waitcnt lgkmcnt(6)
	v_mfma_f32_32x32x16_bf16 v[130:145], v[232:235], v[6:9], v[130:145]
	s_waitcnt lgkmcnt(4)
	v_mfma_f32_32x32x16_bf16 v[82:97], v[228:231], v[10:13], v[82:97]
	global_load_dwordx4 v[206:209], v227, s[92:93] offset:896
	v_mfma_f32_32x32x16_bf16 v[98:113], v[232:235], v[10:13], v[98:113]
	s_waitcnt lgkmcnt(3)
	v_mfma_f32_32x32x16_bf16 v[50:65], v[228:231], v[14:17], v[50:65]
	v_mfma_f32_32x32x16_bf16 v[66:81], v[232:235], v[14:17], v[66:81]
	s_waitcnt lgkmcnt(1)
	v_mfma_f32_32x32x16_bf16 v[18:33], v[228:231], v[236:239], v[18:33]
	v_mfma_f32_32x32x16_bf16 v[34:49], v[232:235], v[236:239], v[34:49]
	s_waitcnt lgkmcnt(0)
	s_barrier
;     ...
;   for (int kt = 0; kt < nk; ++kt) {
;     __syncthreads();
;     if (kt + 1 < nk) {
;       u16* aw = As0 + ((kt + 1) & 1) * 256 * LD;
;       u16* bw = Bs0 + ((kt + 1) & 1) * 256 * LD;
; #pragma unroll
;       for (int i = 0; i < 4; ++i) { *(u32x4*)(aw + (srow + 64 * i) * LD + skc * 8) = ra[i]; *(u32x4*)(bw + (srow + 64 * i) * LD + skc * 8) = rb[i]; }
;     }
;     if (kt + 2 < nk) {
; #pragma unroll
;       for (int i = 0; i < 4; ++i) { ra[i] = *(const u32x4*)(Ag + (size_t)(64 * i) * K + (kt + 2) * 64); rb[i] = *(const u32x4*)(Bg[i] + (kt + 2) * 64); }
;     }
;     __builtin_amdgcn_sched_barrier(0);
;     const u16* as = As0 + (kt & 1) * 256 * LD + (wr * 128 + l31) * LD + h * 8;
;     const u16* bs = Bs0 + (kt & 1) * 256 * LD + (wc * 64 + l31) * LD + h * 8;
;     if (domma)
; #pragma unroll
;     for (int ks = 0; ks < 4; ++ks) {
;       bf16x8 wf[2], xf[4];
; #pragma unroll
;       for (int ct = 0; ct < 2; ++ct) wf[ct] = *(const bf16x8*)(bs + ct * 32 * LD + ks * 16);
; #pragma unroll
;       for (int tt = 0; tt < 4; ++tt) xf[tt] = *(const bf16x8*)(as + tt * 32 * LD + ks * 16);
; #pragma unroll
;       for (int ct = 0; ct < 2; ++ct)
; #pragma unroll
;         for (int tt = 0; tt < 4; ++tt) acc[ct][tt] = __builtin_amdgcn_mfma_f32_32x32x16_bf16(wf[ct], xf[tt], acc[ct][tt], 0, 0, 0);
;     }
	ds_read_b128 v[210:213], v249 offset:36864
	ds_read_b128 v[236:239], v248 offset:36864
	ds_read_b128 v[214:217], v249 offset:41472
	ds_read_b128 v[2:5], v248 offset:41472
	ds_read_b128 v[6:9], v248 offset:46080
	ds_read_b128 v[10:13], v248 offset:50688
	s_waitcnt lgkmcnt(4)
	v_mfma_f32_32x32x16_bf16 v[114:129], v[210:213], v[236:239], v[114:129]
	ds_read_b128 v[228:231], v249 offset:36896
	s_waitcnt lgkmcnt(4)
	v_mfma_f32_32x32x16_bf16 v[130:145], v[214:217], v[236:239], v[130:145]
	ds_read_b128 v[14:17], v248 offset:36896
	s_waitcnt lgkmcnt(4)
	v_mfma_f32_32x32x16_bf16 v[82:97], v[210:213], v[2:5], v[82:97]
	ds_read_b128 v[232:235], v249 offset:41504
	v_mfma_f32_32x32x16_bf16 v[98:113], v[214:217], v[2:5], v[98:113]
	ds_read_b128 v[236:239], v248 offset:41504
	s_waitcnt vmcnt(15)
	ds_write_b128 v250, v[146:149]
	s_waitcnt lgkmcnt(6)
	v_mfma_f32_32x32x16_bf16 v[50:65], v[210:213], v[6:9], v[50:65]
	ds_read_b128 v[2:5], v248 offset:46112
	v_mfma_f32_32x32x16_bf16 v[66:81], v[214:217], v[6:9], v[66:81]
	global_load_dwordx4 v[146:149], v227, s[74:75] offset:1024
	s_waitcnt lgkmcnt(6)
	v_mfma_f32_32x32x16_bf16 v[18:33], v[210:213], v[10:13], v[18:33]
	ds_read_b128 v[6:9], v248 offset:50720
	s_waitcnt vmcnt(15)
	ds_write_b128 v251, v[178:181]
	v_mfma_f32_32x32x16_bf16 v[34:49], v[214:217], v[10:13], v[34:49]
	s_waitcnt lgkmcnt(6)
	v_mfma_f32_32x32x16_bf16 v[114:129], v[228:231], v[14:17], v[114:129]
	ds_read_b128 v[210:213], v249 offset:36928
	global_load_dwordx4 v[178:181], v227, s[82:83] offset:1024
	s_waitcnt lgkmcnt(6)
	v_mfma_f32_32x32x16_bf16 v[130:145], v[232:235], v[14:17], v[130:145]
	ds_read_b128 v[10:13], v248 offset:36928
	s_waitcnt vmcnt(15)
	ds_write_b128 v250, v[150:153] offset:9216
	s_waitcnt lgkmcnt(7)
	v_mfma_f32_32x32x16_bf16 v[82:97], v[228:231], v[236:239], v[82:97]
	ds_read_b128 v[214:217], v249 offset:41536
	v_mfma_f32_32x32x16_bf16 v[98:113], v[232:235], v[236:239], v[98:113]
	ds_read_b128 v[14:17], v248 offset:41536
	global_load_dwordx4 v[150:153], v227, s[76:77] offset:1024
	s_waitcnt lgkmcnt(7)
	v_mfma_f32_32x32x16_bf16 v[50:65], v[228:231], v[2:5], v[50:65]
	ds_read_b128 v[236:239], v248 offset:46144
	s_waitcnt vmcnt(15)
	ds_write_b128 v251, v[182:185] offset:9216
	v_mfma_f32_32x32x16_bf16 v[66:81], v[232:235], v[2:5], v[66:81]
	s_waitcnt lgkmcnt(8)
	v_mfma_f32_32x32x16_bf16 v[18:33], v[228:231], v[6:9], v[18:33]
	ds_read_b128 v[2:5], v248 offset:50752
	global_load_dwordx4 v[182:185], v227, s[84:85] offset:1024
	v_mfma_f32_32x32x16_bf16 v[34:49], v[232:235], v[6:9], v[34:49]
	s_waitcnt vmcnt(15)
	ds_write_b128 v250, v[154:157] offset:18432
	s_waitcnt lgkmcnt(7)
	v_mfma_f32_32x32x16_bf16 v[114:129], v[210:213], v[10:13], v[114:129]
	ds_read_b128 v[228:231], v249 offset:36960
	s_waitcnt lgkmcnt(6)
	v_mfma_f32_32x32x16_bf16 v[130:145], v[214:217], v[10:13], v[130:145]
	ds_read_b128 v[6:9], v248 offset:36960
	global_load_dwordx4 v[154:157], v227, s[78:79] offset:1024
	s_waitcnt lgkmcnt(6)
	v_mfma_f32_32x32x16_bf16 v[82:97], v[210:213], v[14:17], v[82:97]
	ds_read_b128 v[232:235], v249 offset:41568
	s_waitcnt vmcnt(15)
	ds_write_b128 v251, v[186:189] offset:18432
	v_mfma_f32_32x32x16_bf16 v[98:113], v[214:217], v[14:17], v[98:113]
	ds_read_b128 v[10:13], v248 offset:41568
	s_waitcnt lgkmcnt(8)
	v_mfma_f32_32x32x16_bf16 v[50:65], v[210:213], v[236:239], v[50:65]
	ds_read_b128 v[14:17], v248 offset:46176
	global_load_dwordx4 v[186:189], v227, s[86:87] offset:1024
	v_mfma_f32_32x32x16_bf16 v[66:81], v[214:217], v[236:239], v[66:81]
	s_waitcnt vmcnt(15)
	ds_write_b128 v250, v[158:161] offset:27648
	s_waitcnt lgkmcnt(8)
	v_mfma_f32_32x32x16_bf16 v[18:33], v[210:213], v[2:5], v[18:33]
	ds_read_b128 v[236:239], v248 offset:50784
	v_mfma_f32_32x32x16_bf16 v[34:49], v[214:217], v[2:5], v[34:49]
	global_load_dwordx4 v[158:161], v227, s[80:81] offset:1024
	s_waitcnt lgkmcnt(6)
	v_mfma_f32_32x32x16_bf16 v[114:129], v[228:231], v[6:9], v[114:129]
	s_waitcnt vmcnt(15)
	ds_write_b128 v251, v[190:193] offset:27648
	s_waitcnt lgkmcnt(6)
	v_mfma_f32_32x32x16_bf16 v[130:145], v[232:235], v[6:9], v[130:145]
	s_waitcnt lgkmcnt(4)
	v_mfma_f32_32x32x16_bf16 v[82:97], v[228:231], v[10:13], v[82:97]
	global_load_dwordx4 v[190:193], v227, s[92:93] offset:1024
	v_mfma_f32_32x32x16_bf16 v[98:113], v[232:235], v[10:13], v[98:113]
	s_waitcnt lgkmcnt(3)
	v_mfma_f32_32x32x16_bf16 v[50:65], v[228:231], v[14:17], v[50:65]
	v_mfma_f32_32x32x16_bf16 v[66:81], v[232:235], v[14:17], v[66:81]
	s_waitcnt lgkmcnt(1)
	v_mfma_f32_32x32x16_bf16 v[18:33], v[228:231], v[236:239], v[18:33]
	v_mfma_f32_32x32x16_bf16 v[34:49], v[232:235], v[236:239], v[34:49]
	s_waitcnt lgkmcnt(0)
	s_barrier
;     ...
;   for (int kt = 0; kt < nk; ++kt) {
;     __syncthreads();
;     if (kt + 1 < nk) {
;       u16* aw = As0 + ((kt + 1) & 1) * 256 * LD;
;       u16* bw = Bs0 + ((kt + 1) & 1) * 256 * LD;
; #pragma unroll
;       for (int i = 0; i < 4; ++i) { *(u32x4*)(aw + (srow + 64 * i) * LD + skc * 8) = ra[i]; *(u32x4*)(bw + (srow + 64 * i) * LD + skc * 8) = rb[i]; }
;     }
;     if (kt + 2 < nk) {
; #pragma unroll
;       for (int i = 0; i < 4; ++i) { ra[i] = *(const u32x4*)(Ag + (size_t)(64 * i) * K + (kt + 2) * 64); rb[i] = *(const u32x4*)(Bg[i] + (kt + 2) * 64); }
;     }
;     __builtin_amdgcn_sched_barrier(0);
;     const u16* as = As0 + (kt & 1) * 256 * LD + (wr * 128 + l31) * LD + h * 8;
;     const u16* bs = Bs0 + (kt & 1) * 256 * LD + (wc * 64 + l31) * LD + h * 8;
;     if (domma)
; #pragma unroll
;     for (int ks = 0; ks < 4; ++ks) {
;       bf16x8 wf[2], xf[4];
; #pragma unroll
;       for (int ct = 0; ct < 2; ++ct) wf[ct] = *(const bf16x8*)(bs + ct * 32 * LD + ks * 16);
; #pragma unroll
;       for (int tt = 0; tt < 4; ++tt) xf[tt] = *(const bf16x8*)(as + tt * 32 * LD + ks * 16);
; #pragma unroll
;       for (int ct = 0; ct < 2; ++ct)
; #pragma unroll
;         for (int tt = 0; tt < 4; ++tt) acc[ct][tt] = __builtin_amdgcn_mfma_f32_32x32x16_bf16(wf[ct], xf[tt], acc[ct][tt], 0, 0, 0);
;     }
	ds_read_b128 v[210:213], v249
	ds_read_b128 v[236:239], v248
	ds_read_b128 v[214:217], v249 offset:4608
	ds_read_b128 v[2:5], v248 offset:4608
	ds_read_b128 v[6:9], v248 offset:9216
	ds_read_b128 v[10:13], v248 offset:13824
	s_waitcnt lgkmcnt(4)
	v_mfma_f32_32x32x16_bf16 v[114:129], v[210:213], v[236:239], v[114:129]
	ds_read_b128 v[228:231], v249 offset:32
	s_waitcnt lgkmcnt(4)
	v_mfma_f32_32x32x16_bf16 v[130:145], v[214:217], v[236:239], v[130:145]
	ds_read_b128 v[14:17], v248 offset:32
	s_waitcnt lgkmcnt(4)
	v_mfma_f32_32x32x16_bf16 v[82:97], v[210:213], v[2:5], v[82:97]
	ds_read_b128 v[232:235], v249 offset:4640
	v_mfma_f32_32x32x16_bf16 v[98:113], v[214:217], v[2:5], v[98:113]
	ds_read_b128 v[236:239], v248 offset:4640
	s_waitcnt vmcnt(15)
	ds_write_b128 v250, v[162:165] offset:36864
	s_waitcnt lgkmcnt(6)
	v_mfma_f32_32x32x16_bf16 v[50:65], v[210:213], v[6:9], v[50:65]
	ds_read_b128 v[2:5], v248 offset:9248
	v_mfma_f32_32x32x16_bf16 v[66:81], v[214:217], v[6:9], v[66:81]
	global_load_dwordx4 v[162:165], v227, s[74:75] offset:1152
	s_waitcnt lgkmcnt(6)
	v_mfma_f32_32x32x16_bf16 v[18:33], v[210:213], v[10:13], v[18:33]
	ds_read_b128 v[6:9], v248 offset:13856
	s_waitcnt vmcnt(15)
	ds_write_b128 v251, v[194:197] offset:36864
	v_mfma_f32_32x32x16_bf16 v[34:49], v[214:217], v[10:13], v[34:49]
	s_waitcnt lgkmcnt(6)
	v_mfma_f32_32x32x16_bf16 v[114:129], v[228:231], v[14:17], v[114:129]
	ds_read_b128 v[210:213], v249 offset:64
	global_load_dwordx4 v[194:197], v227, s[82:83] offset:1152
	s_waitcnt lgkmcnt(6)
	v_mfma_f32_32x32x16_bf16 v[130:145], v[232:235], v[14:17], v[130:145]
	ds_read_b128 v[10:13], v248 offset:64
	s_waitcnt vmcnt(15)
	ds_write_b128 v250, v[166:169] offset:46080
	s_waitcnt lgkmcnt(7)
	v_mfma_f32_32x32x16_bf16 v[82:97], v[228:231], v[236:239], v[82:97]
	ds_read_b128 v[214:217], v249 offset:4672
	v_mfma_f32_32x32x16_bf16 v[98:113], v[232:235], v[236:239], v[98:113]
	ds_read_b128 v[14:17], v248 offset:4672
	global_load_dwordx4 v[166:169], v227, s[76:77] offset:1152
	s_waitcnt lgkmcnt(7)
	v_mfma_f32_32x32x16_bf16 v[50:65], v[228:231], v[2:5], v[50:65]
	ds_read_b128 v[236:239], v248 offset:9280
	s_waitcnt vmcnt(15)
	ds_write_b128 v251, v[198:201] offset:46080
	v_mfma_f32_32x32x16_bf16 v[66:81], v[232:235], v[2:5], v[66:81]
	s_waitcnt lgkmcnt(8)
	v_mfma_f32_32x32x16_bf16 v[18:33], v[228:231], v[6:9], v[18:33]
	ds_read_b128 v[2:5], v248 offset:13888
	global_load_dwordx4 v[198:201], v227, s[84:85] offset:1152
	v_mfma_f32_32x32x16_bf16 v[34:49], v[232:235], v[6:9], v[34:49]
	s_waitcnt vmcnt(15)
	ds_write_b128 v250, v[170:173] offset:55296
	s_waitcnt lgkmcnt(7)
	v_mfma_f32_32x32x16_bf16 v[114:129], v[210:213], v[10:13], v[114:129]
	ds_read_b128 v[228:231], v249 offset:96
	s_waitcnt lgkmcnt(6)
	v_mfma_f32_32x32x16_bf16 v[130:145], v[214:217], v[10:13], v[130:145]
	ds_read_b128 v[6:9], v248 offset:96
	global_load_dwordx4 v[170:173], v227, s[78:79] offset:1152
	s_waitcnt lgkmcnt(6)
	v_mfma_f32_32x32x16_bf16 v[82:97], v[210:213], v[14:17], v[82:97]
	ds_read_b128 v[232:235], v249 offset:4704
	s_waitcnt vmcnt(15)
	ds_write_b128 v251, v[202:205] offset:55296
	v_mfma_f32_32x32x16_bf16 v[98:113], v[214:217], v[14:17], v[98:113]
	ds_read_b128 v[10:13], v248 offset:4704
	s_waitcnt lgkmcnt(8)
	v_mfma_f32_32x32x16_bf16 v[50:65], v[210:213], v[236:239], v[50:65]
	ds_read_b128 v[14:17], v248 offset:9312
	global_load_dwordx4 v[202:205], v227, s[86:87] offset:1152
	v_mfma_f32_32x32x16_bf16 v[66:81], v[214:217], v[236:239], v[66:81]
	s_waitcnt vmcnt(15)
	ds_write_b128 v250, v[174:177] offset:64512
	s_waitcnt lgkmcnt(8)
	v_mfma_f32_32x32x16_bf16 v[18:33], v[210:213], v[2:5], v[18:33]
	ds_read_b128 v[236:239], v248 offset:13920
	v_mfma_f32_32x32x16_bf16 v[34:49], v[214:217], v[2:5], v[34:49]
	global_load_dwordx4 v[174:177], v227, s[80:81] offset:1152
	s_waitcnt lgkmcnt(6)
	v_mfma_f32_32x32x16_bf16 v[114:129], v[228:231], v[6:9], v[114:129]
	s_waitcnt vmcnt(15)
	ds_write_b128 v251, v[206:209] offset:64512
	s_waitcnt lgkmcnt(6)
	v_mfma_f32_32x32x16_bf16 v[130:145], v[232:235], v[6:9], v[130:145]
	s_waitcnt lgkmcnt(4)
	v_mfma_f32_32x32x16_bf16 v[82:97], v[228:231], v[10:13], v[82:97]
	global_load_dwordx4 v[206:209], v227, s[92:93] offset:1152
	v_mfma_f32_32x32x16_bf16 v[98:113], v[232:235], v[10:13], v[98:113]
	s_waitcnt lgkmcnt(3)
	v_mfma_f32_32x32x16_bf16 v[50:65], v[228:231], v[14:17], v[50:65]
	v_mfma_f32_32x32x16_bf16 v[66:81], v[232:235], v[14:17], v[66:81]
	s_waitcnt lgkmcnt(1)
	v_mfma_f32_32x32x16_bf16 v[18:33], v[228:231], v[236:239], v[18:33]
	v_mfma_f32_32x32x16_bf16 v[34:49], v[232:235], v[236:239], v[34:49]
	s_waitcnt lgkmcnt(0)
	s_barrier
;     ...
;   for (int kt = 0; kt < nk; ++kt) {
;     __syncthreads();
;     if (kt + 1 < nk) {
;       u16* aw = As0 + ((kt + 1) & 1) * 256 * LD;
;       u16* bw = Bs0 + ((kt + 1) & 1) * 256 * LD;
; #pragma unroll
;       for (int i = 0; i < 4; ++i) { *(u32x4*)(aw + (srow + 64 * i) * LD + skc * 8) = ra[i]; *(u32x4*)(bw + (srow + 64 * i) * LD + skc * 8) = rb[i]; }
;     }
;     if (kt + 2 < nk) {
; #pragma unroll
;       for (int i = 0; i < 4; ++i) { ra[i] = *(const u32x4*)(Ag + (size_t)(64 * i) * K + (kt + 2) * 64); rb[i] = *(const u32x4*)(Bg[i] + (kt + 2) * 64); }
;     }
;     __builtin_amdgcn_sched_barrier(0);
;     const u16* as = As0 + (kt & 1) * 256 * LD + (wr * 128 + l31) * LD + h * 8;
;     const u16* bs = Bs0 + (kt & 1) * 256 * LD + (wc * 64 + l31) * LD + h * 8;
;     if (domma)
; #pragma unroll
;     for (int ks = 0; ks < 4; ++ks) {
;       bf16x8 wf[2], xf[4];
; #pragma unroll
;       for (int ct = 0; ct < 2; ++ct) wf[ct] = *(const bf16x8*)(bs + ct * 32 * LD + ks * 16);
; #pragma unroll
;       for (int tt = 0; tt < 4; ++tt) xf[tt] = *(const bf16x8*)(as + tt * 32 * LD + ks * 16);
; #pragma unroll
;       for (int ct = 0; ct < 2; ++ct)
; #pragma unroll
;         for (int tt = 0; tt < 4; ++tt) acc[ct][tt] = __builtin_amdgcn_mfma_f32_32x32x16_bf16(wf[ct], xf[tt], acc[ct][tt], 0, 0, 0);
;     }
	ds_read_b128 v[210:213], v249 offset:36864
	ds_read_b128 v[236:239], v248 offset:36864
	ds_read_b128 v[214:217], v249 offset:41472
	ds_read_b128 v[2:5], v248 offset:41472
	ds_read_b128 v[6:9], v248 offset:46080
	ds_read_b128 v[10:13], v248 offset:50688
	s_waitcnt lgkmcnt(4)
	v_mfma_f32_32x32x16_bf16 v[114:129], v[210:213], v[236:239], v[114:129]
	ds_read_b128 v[228:231], v249 offset:36896
	s_waitcnt lgkmcnt(4)
	v_mfma_f32_32x32x16_bf16 v[130:145], v[214:217], v[236:239], v[130:145]
	ds_read_b128 v[14:17], v248 offset:36896
	s_waitcnt lgkmcnt(4)
	v_mfma_f32_32x32x16_bf16 v[82:97], v[210:213], v[2:5], v[82:97]
	ds_read_b128 v[232:235], v249 offset:41504
	v_mfma_f32_32x32x16_bf16 v[98:113], v[214:217], v[2:5], v[98:113]
	ds_read_b128 v[236:239], v248 offset:41504
	s_waitcnt vmcnt(15)
	ds_write_b128 v250, v[146:149]
	s_waitcnt lgkmcnt(6)
	v_mfma_f32_32x32x16_bf16 v[50:65], v[210:213], v[6:9], v[50:65]
	ds_read_b128 v[2:5], v248 offset:46112
	v_mfma_f32_32x32x16_bf16 v[66:81], v[214:217], v[6:9], v[66:81]
	global_load_dwordx4 v[146:149], v227, s[74:75] offset:1280
	s_waitcnt lgkmcnt(6)
	v_mfma_f32_32x32x16_bf16 v[18:33], v[210:213], v[10:13], v[18:33]
	ds_read_b128 v[6:9], v248 offset:50720
	s_waitcnt vmcnt(15)
	ds_write_b128 v251, v[178:181]
	v_mfma_f32_32x32x16_bf16 v[34:49], v[214:217], v[10:13], v[34:49]
	s_waitcnt lgkmcnt(6)
	v_mfma_f32_32x32x16_bf16 v[114:129], v[228:231], v[14:17], v[114:129]
	ds_read_b128 v[210:213], v249 offset:36928
	global_load_dwordx4 v[178:181], v227, s[82:83] offset:1280
	s_waitcnt lgkmcnt(6)
	v_mfma_f32_32x32x16_bf16 v[130:145], v[232:235], v[14:17], v[130:145]
	ds_read_b128 v[10:13], v248 offset:36928
	s_waitcnt vmcnt(15)
	ds_write_b128 v250, v[150:153] offset:9216
	s_waitcnt lgkmcnt(7)
	v_mfma_f32_32x32x16_bf16 v[82:97], v[228:231], v[236:239], v[82:97]
	ds_read_b128 v[214:217], v249 offset:41536
	v_mfma_f32_32x32x16_bf16 v[98:113], v[232:235], v[236:239], v[98:113]
	ds_read_b128 v[14:17], v248 offset:41536
	global_load_dwordx4 v[150:153], v227, s[76:77] offset:1280
	s_waitcnt lgkmcnt(7)
	v_mfma_f32_32x32x16_bf16 v[50:65], v[228:231], v[2:5], v[50:65]
	ds_read_b128 v[236:239], v248 offset:46144
	s_waitcnt vmcnt(15)
	ds_write_b128 v251, v[182:185] offset:9216
	v_mfma_f32_32x32x16_bf16 v[66:81], v[232:235], v[2:5], v[66:81]
	s_waitcnt lgkmcnt(8)
	v_mfma_f32_32x32x16_bf16 v[18:33], v[228:231], v[6:9], v[18:33]
	ds_read_b128 v[2:5], v248 offset:50752
	global_load_dwordx4 v[182:185], v227, s[84:85] offset:1280
	v_mfma_f32_32x32x16_bf16 v[34:49], v[232:235], v[6:9], v[34:49]
	s_waitcnt vmcnt(15)
	ds_write_b128 v250, v[154:157] offset:18432
	s_waitcnt lgkmcnt(7)
	v_mfma_f32_32x32x16_bf16 v[114:129], v[210:213], v[10:13], v[114:129]
	ds_read_b128 v[228:231], v249 offset:36960
	s_waitcnt lgkmcnt(6)
	v_mfma_f32_32x32x16_bf16 v[130:145], v[214:217], v[10:13], v[130:145]
	ds_read_b128 v[6:9], v248 offset:36960
	global_load_dwordx4 v[154:157], v227, s[78:79] offset:1280
	s_waitcnt lgkmcnt(6)
	v_mfma_f32_32x32x16_bf16 v[82:97], v[210:213], v[14:17], v[82:97]
	ds_read_b128 v[232:235], v249 offset:41568
	s_waitcnt vmcnt(15)
	ds_write_b128 v251, v[186:189] offset:18432
	v_mfma_f32_32x32x16_bf16 v[98:113], v[214:217], v[14:17], v[98:113]
	ds_read_b128 v[10:13], v248 offset:41568
	s_waitcnt lgkmcnt(8)
	v_mfma_f32_32x32x16_bf16 v[50:65], v[210:213], v[236:239], v[50:65]
	ds_read_b128 v[14:17], v248 offset:46176
	global_load_dwordx4 v[186:189], v227, s[86:87] offset:1280
	v_mfma_f32_32x32x16_bf16 v[66:81], v[214:217], v[236:239], v[66:81]
	s_waitcnt vmcnt(15)
	ds_write_b128 v250, v[158:161] offset:27648
	s_waitcnt lgkmcnt(8)
	v_mfma_f32_32x32x16_bf16 v[18:33], v[210:213], v[2:5], v[18:33]
	ds_read_b128 v[236:239], v248 offset:50784
	v_mfma_f32_32x32x16_bf16 v[34:49], v[214:217], v[2:5], v[34:49]
	global_load_dwordx4 v[158:161], v227, s[80:81] offset:1280
	s_waitcnt lgkmcnt(6)
	v_mfma_f32_32x32x16_bf16 v[114:129], v[228:231], v[6:9], v[114:129]
	s_waitcnt vmcnt(15)
	ds_write_b128 v251, v[190:193] offset:27648
	s_waitcnt lgkmcnt(6)
	v_mfma_f32_32x32x16_bf16 v[130:145], v[232:235], v[6:9], v[130:145]
	s_waitcnt lgkmcnt(4)
	v_mfma_f32_32x32x16_bf16 v[82:97], v[228:231], v[10:13], v[82:97]
	global_load_dwordx4 v[190:193], v227, s[92:93] offset:1280
	v_mfma_f32_32x32x16_bf16 v[98:113], v[232:235], v[10:13], v[98:113]
	s_waitcnt lgkmcnt(3)
	v_mfma_f32_32x32x16_bf16 v[50:65], v[228:231], v[14:17], v[50:65]
	v_mfma_f32_32x32x16_bf16 v[66:81], v[232:235], v[14:17], v[66:81]
	s_waitcnt lgkmcnt(1)
	v_mfma_f32_32x32x16_bf16 v[18:33], v[228:231], v[236:239], v[18:33]
	v_mfma_f32_32x32x16_bf16 v[34:49], v[232:235], v[236:239], v[34:49]
	s_waitcnt lgkmcnt(0)
	s_barrier
;     ...
;   for (int kt = 0; kt < nk; ++kt) {
;     __syncthreads();
;     if (kt + 1 < nk) {
;       u16* aw = As0 + ((kt + 1) & 1) * 256 * LD;
;       u16* bw = Bs0 + ((kt + 1) & 1) * 256 * LD;
; #pragma unroll
;       for (int i = 0; i < 4; ++i) { *(u32x4*)(aw + (srow + 64 * i) * LD + skc * 8) = ra[i]; *(u32x4*)(bw + (srow + 64 * i) * LD + skc * 8) = rb[i]; }
;     }
;     if (kt + 2 < nk) {
; #pragma unroll
;       for (int i = 0; i < 4; ++i) { ra[i] = *(const u32x4*)(Ag + (size_t)(64 * i) * K + (kt + 2) * 64); rb[i] = *(const u32x4*)(Bg[i] + (kt + 2) * 64); }
;     }
;     __builtin_amdgcn_sched_barrier(0);
;     const u16* as = As0 + (kt & 1) * 256 * LD + (wr * 128 + l31) * LD + h * 8;
;     const u16* bs = Bs0 + (kt & 1) * 256 * LD + (wc * 64 + l31) * LD + h * 8;
;     if (domma)
; #pragma unroll
;     for (int ks = 0; ks < 4; ++ks) {
;       bf16x8 wf[2], xf[4];
; #pragma unroll
;       for (int ct = 0; ct < 2; ++ct) wf[ct] = *(const bf16x8*)(bs + ct * 32 * LD + ks * 16);
; #pragma unroll
;       for (int tt = 0; tt < 4; ++tt) xf[tt] = *(const bf16x8*)(as + tt * 32 * LD + ks * 16);
; #pragma unroll
;       for (int ct = 0; ct < 2; ++ct)
; #pragma unroll
;         for (int tt = 0; tt < 4; ++tt) acc[ct][tt] = __builtin_amdgcn_mfma_f32_32x32x16_bf16(wf[ct], xf[tt], acc[ct][tt], 0, 0, 0);
;     }
	ds_read_b128 v[210:213], v249
	ds_read_b128 v[236:239], v248
	ds_read_b128 v[214:217], v249 offset:4608
	ds_read_b128 v[2:5], v248 offset:4608
	ds_read_b128 v[6:9], v248 offset:9216
	ds_read_b128 v[10:13], v248 offset:13824
	s_waitcnt lgkmcnt(4)
	v_mfma_f32_32x32x16_bf16 v[114:129], v[210:213], v[236:239], v[114:129]
	ds_read_b128 v[228:231], v249 offset:32
	s_waitcnt lgkmcnt(4)
	v_mfma_f32_32x32x16_bf16 v[130:145], v[214:217], v[236:239], v[130:145]
	ds_read_b128 v[14:17], v248 offset:32
	s_waitcnt lgkmcnt(4)
	v_mfma_f32_32x32x16_bf16 v[82:97], v[210:213], v[2:5], v[82:97]
	ds_read_b128 v[232:235], v249 offset:4640
	v_mfma_f32_32x32x16_bf16 v[98:113], v[214:217], v[2:5], v[98:113]
	ds_read_b128 v[236:239], v248 offset:4640
	s_waitcnt vmcnt(15)
	ds_write_b128 v250, v[162:165] offset:36864
	s_waitcnt lgkmcnt(6)
	v_mfma_f32_32x32x16_bf16 v[50:65], v[210:213], v[6:9], v[50:65]
	ds_read_b128 v[2:5], v248 offset:9248
	v_mfma_f32_32x32x16_bf16 v[66:81], v[214:217], v[6:9], v[66:81]
	global_load_dwordx4 v[162:165], v227, s[74:75] offset:1408
	s_waitcnt lgkmcnt(6)
	v_mfma_f32_32x32x16_bf16 v[18:33], v[210:213], v[10:13], v[18:33]
	ds_read_b128 v[6:9], v248 offset:13856
	s_waitcnt vmcnt(15)
	ds_write_b128 v251, v[194:197] offset:36864
	v_mfma_f32_32x32x16_bf16 v[34:49], v[214:217], v[10:13], v[34:49]
	s_waitcnt lgkmcnt(6)
	v_mfma_f32_32x32x16_bf16 v[114:129], v[228:231], v[14:17], v[114:129]
	ds_read_b128 v[210:213], v249 offset:64
	global_load_dwordx4 v[194:197], v227, s[82:83] offset:1408
	s_waitcnt lgkmcnt(6)
	v_mfma_f32_32x32x16_bf16 v[130:145], v[232:235], v[14:17], v[130:145]
	ds_read_b128 v[10:13], v248 offset:64
	s_waitcnt vmcnt(15)
	ds_write_b128 v250, v[166:169] offset:46080
	s_waitcnt lgkmcnt(7)
	v_mfma_f32_32x32x16_bf16 v[82:97], v[228:231], v[236:239], v[82:97]
	ds_read_b128 v[214:217], v249 offset:4672
	v_mfma_f32_32x32x16_bf16 v[98:113], v[232:235], v[236:239], v[98:113]
	ds_read_b128 v[14:17], v248 offset:4672
	global_load_dwordx4 v[166:169], v227, s[76:77] offset:1408
	s_waitcnt lgkmcnt(7)
	v_mfma_f32_32x32x16_bf16 v[50:65], v[228:231], v[2:5], v[50:65]
	ds_read_b128 v[236:239], v248 offset:9280
	s_waitcnt vmcnt(15)
	ds_write_b128 v251, v[198:201] offset:46080
	v_mfma_f32_32x32x16_bf16 v[66:81], v[232:235], v[2:5], v[66:81]
	s_waitcnt lgkmcnt(8)
	v_mfma_f32_32x32x16_bf16 v[18:33], v[228:231], v[6:9], v[18:33]
	ds_read_b128 v[2:5], v248 offset:13888
	global_load_dwordx4 v[198:201], v227, s[84:85] offset:1408
	v_mfma_f32_32x32x16_bf16 v[34:49], v[232:235], v[6:9], v[34:49]
	s_waitcnt vmcnt(15)
	ds_write_b128 v250, v[170:173] offset:55296
	s_waitcnt lgkmcnt(7)
	v_mfma_f32_32x32x16_bf16 v[114:129], v[210:213], v[10:13], v[114:129]
	ds_read_b128 v[228:231], v249 offset:96
	s_waitcnt lgkmcnt(6)
	v_mfma_f32_32x32x16_bf16 v[130:145], v[214:217], v[10:13], v[130:145]
	ds_read_b128 v[6:9], v248 offset:96
	global_load_dwordx4 v[170:173], v227, s[78:79] offset:1408
	s_waitcnt lgkmcnt(6)
	v_mfma_f32_32x32x16_bf16 v[82:97], v[210:213], v[14:17], v[82:97]
	ds_read_b128 v[232:235], v249 offset:4704
	s_waitcnt vmcnt(15)
	ds_write_b128 v251, v[202:205] offset:55296
	v_mfma_f32_32x32x16_bf16 v[98:113], v[214:217], v[14:17], v[98:113]
	ds_read_b128 v[10:13], v248 offset:4704
	s_waitcnt lgkmcnt(8)
	v_mfma_f32_32x32x16_bf16 v[50:65], v[210:213], v[236:239], v[50:65]
	ds_read_b128 v[14:17], v248 offset:9312
	global_load_dwordx4 v[202:205], v227, s[86:87] offset:1408
	v_mfma_f32_32x32x16_bf16 v[66:81], v[214:217], v[236:239], v[66:81]
	s_waitcnt vmcnt(15)
	ds_write_b128 v250, v[174:177] offset:64512
	s_waitcnt lgkmcnt(8)
	v_mfma_f32_32x32x16_bf16 v[18:33], v[210:213], v[2:5], v[18:33]
	ds_read_b128 v[236:239], v248 offset:13920
	v_mfma_f32_32x32x16_bf16 v[34:49], v[214:217], v[2:5], v[34:49]
	global_load_dwordx4 v[174:177], v227, s[80:81] offset:1408
	s_waitcnt lgkmcnt(6)
	v_mfma_f32_32x32x16_bf16 v[114:129], v[228:231], v[6:9], v[114:129]
	s_waitcnt vmcnt(15)
	ds_write_b128 v251, v[206:209] offset:64512
	s_waitcnt lgkmcnt(6)
	v_mfma_f32_32x32x16_bf16 v[130:145], v[232:235], v[6:9], v[130:145]
	s_waitcnt lgkmcnt(4)
	v_mfma_f32_32x32x16_bf16 v[82:97], v[228:231], v[10:13], v[82:97]
	global_load_dwordx4 v[206:209], v227, s[92:93] offset:1408
	v_mfma_f32_32x32x16_bf16 v[98:113], v[232:235], v[10:13], v[98:113]
	s_waitcnt lgkmcnt(3)
	v_mfma_f32_32x32x16_bf16 v[50:65], v[228:231], v[14:17], v[50:65]
	v_mfma_f32_32x32x16_bf16 v[66:81], v[232:235], v[14:17], v[66:81]
	s_waitcnt lgkmcnt(1)
	v_mfma_f32_32x32x16_bf16 v[18:33], v[228:231], v[236:239], v[18:33]
	v_mfma_f32_32x32x16_bf16 v[34:49], v[232:235], v[236:239], v[34:49]
	s_waitcnt lgkmcnt(0)
	s_barrier
;     ...
;   for (int kt = 0; kt < nk; ++kt) {
;     __syncthreads();
;     if (kt + 1 < nk) {
;       u16* aw = As0 + ((kt + 1) & 1) * 256 * LD;
;       u16* bw = Bs0 + ((kt + 1) & 1) * 256 * LD;
; #pragma unroll
;       for (int i = 0; i < 4; ++i) { *(u32x4*)(aw + (srow + 64 * i) * LD + skc * 8) = ra[i]; *(u32x4*)(bw + (srow + 64 * i) * LD + skc * 8) = rb[i]; }
;     }
;     if (kt + 2 < nk) {
; #pragma unroll
;       for (int i = 0; i < 4; ++i) { ra[i] = *(const u32x4*)(Ag + (size_t)(64 * i) * K + (kt + 2) * 64); rb[i] = *(const u32x4*)(Bg[i] + (kt + 2) * 64); }
;     }
;     __builtin_amdgcn_sched_barrier(0);
;     const u16* as = As0 + (kt & 1) * 256 * LD + (wr * 128 + l31) * LD + h * 8;
;     const u16* bs = Bs0 + (kt & 1) * 256 * LD + (wc * 64 + l31) * LD + h * 8;
;     if (domma)
; #pragma unroll
;     for (int ks = 0; ks < 4; ++ks) {
;       bf16x8 wf[2], xf[4];
; #pragma unroll
;       for (int ct = 0; ct < 2; ++ct) wf[ct] = *(const bf16x8*)(bs + ct * 32 * LD + ks * 16);
; #pragma unroll
;       for (int tt = 0; tt < 4; ++tt) xf[tt] = *(const bf16x8*)(as + tt * 32 * LD + ks * 16);
; #pragma unroll
;       for (int ct = 0; ct < 2; ++ct)
; #pragma unroll
;         for (int tt = 0; tt < 4; ++tt) acc[ct][tt] = __builtin_amdgcn_mfma_f32_32x32x16_bf16(wf[ct], xf[tt], acc[ct][tt], 0, 0, 0);
;     }
	ds_read_b128 v[210:213], v249 offset:36864
	ds_read_b128 v[236:239], v248 offset:36864
	ds_read_b128 v[214:217], v249 offset:41472
	ds_read_b128 v[2:5], v248 offset:41472
	ds_read_b128 v[6:9], v248 offset:46080
	ds_read_b128 v[10:13], v248 offset:50688
	s_waitcnt lgkmcnt(4)
	v_mfma_f32_32x32x16_bf16 v[114:129], v[210:213], v[236:239], v[114:129]
	ds_read_b128 v[228:231], v249 offset:36896
	s_waitcnt lgkmcnt(4)
	v_mfma_f32_32x32x16_bf16 v[130:145], v[214:217], v[236:239], v[130:145]
	ds_read_b128 v[14:17], v248 offset:36896
	s_waitcnt lgkmcnt(4)
	v_mfma_f32_32x32x16_bf16 v[82:97], v[210:213], v[2:5], v[82:97]
	ds_read_b128 v[232:235], v249 offset:41504
	v_mfma_f32_32x32x16_bf16 v[98:113], v[214:217], v[2:5], v[98:113]
	ds_read_b128 v[236:239], v248 offset:41504
	s_waitcnt vmcnt(15)
	ds_write_b128 v250, v[146:149]
	s_waitcnt lgkmcnt(6)
	v_mfma_f32_32x32x16_bf16 v[50:65], v[210:213], v[6:9], v[50:65]
	ds_read_b128 v[2:5], v248 offset:46112
	v_mfma_f32_32x32x16_bf16 v[66:81], v[214:217], v[6:9], v[66:81]
	global_load_dwordx4 v[146:149], v227, s[74:75] offset:1536
	s_waitcnt lgkmcnt(6)
	v_mfma_f32_32x32x16_bf16 v[18:33], v[210:213], v[10:13], v[18:33]
	ds_read_b128 v[6:9], v248 offset:50720
	s_waitcnt vmcnt(15)
	ds_write_b128 v251, v[178:181]
	v_mfma_f32_32x32x16_bf16 v[34:49], v[214:217], v[10:13], v[34:49]
	s_waitcnt lgkmcnt(6)
	v_mfma_f32_32x32x16_bf16 v[114:129], v[228:231], v[14:17], v[114:129]
	ds_read_b128 v[210:213], v249 offset:36928
	global_load_dwordx4 v[178:181], v227, s[82:83] offset:1536
	s_waitcnt lgkmcnt(6)
	v_mfma_f32_32x32x16_bf16 v[130:145], v[232:235], v[14:17], v[130:145]
	ds_read_b128 v[10:13], v248 offset:36928
	s_waitcnt vmcnt(15)
	ds_write_b128 v250, v[150:153] offset:9216
	s_waitcnt lgkmcnt(7)
	v_mfma_f32_32x32x16_bf16 v[82:97], v[228:231], v[236:239], v[82:97]
	ds_read_b128 v[214:217], v249 offset:41536
	v_mfma_f32_32x32x16_bf16 v[98:113], v[232:235], v[236:239], v[98:113]
	ds_read_b128 v[14:17], v248 offset:41536
	global_load_dwordx4 v[150:153], v227, s[76:77] offset:1536
	s_waitcnt lgkmcnt(7)
	v_mfma_f32_32x32x16_bf16 v[50:65], v[228:231], v[2:5], v[50:65]
	ds_read_b128 v[236:239], v248 offset:46144
	s_waitcnt vmcnt(15)
	ds_write_b128 v251, v[182:185] offset:9216
	v_mfma_f32_32x32x16_bf16 v[66:81], v[232:235], v[2:5], v[66:81]
	s_waitcnt lgkmcnt(8)
	v_mfma_f32_32x32x16_bf16 v[18:33], v[228:231], v[6:9], v[18:33]
	ds_read_b128 v[2:5], v248 offset:50752
	global_load_dwordx4 v[182:185], v227, s[84:85] offset:1536
	v_mfma_f32_32x32x16_bf16 v[34:49], v[232:235], v[6:9], v[34:49]
	s_waitcnt vmcnt(15)
	ds_write_b128 v250, v[154:157] offset:18432
	s_waitcnt lgkmcnt(7)
	v_mfma_f32_32x32x16_bf16 v[114:129], v[210:213], v[10:13], v[114:129]
	ds_read_b128 v[228:231], v249 offset:36960
	s_waitcnt lgkmcnt(6)
	v_mfma_f32_32x32x16_bf16 v[130:145], v[214:217], v[10:13], v[130:145]
	ds_read_b128 v[6:9], v248 offset:36960
	global_load_dwordx4 v[154:157], v227, s[78:79] offset:1536
	s_waitcnt lgkmcnt(6)
	v_mfma_f32_32x32x16_bf16 v[82:97], v[210:213], v[14:17], v[82:97]
	ds_read_b128 v[232:235], v249 offset:41568
	s_waitcnt vmcnt(15)
	ds_write_b128 v251, v[186:189] offset:18432
	v_mfma_f32_32x32x16_bf16 v[98:113], v[214:217], v[14:17], v[98:113]
	ds_read_b128 v[10:13], v248 offset:41568
	s_waitcnt lgkmcnt(8)
	v_mfma_f32_32x32x16_bf16 v[50:65], v[210:213], v[236:239], v[50:65]
	ds_read_b128 v[14:17], v248 offset:46176
	global_load_dwordx4 v[186:189], v227, s[86:87] offset:1536
	v_mfma_f32_32x32x16_bf16 v[66:81], v[214:217], v[236:239], v[66:81]
	s_waitcnt vmcnt(15)
	ds_write_b128 v250, v[158:161] offset:27648
	s_waitcnt lgkmcnt(8)
	v_mfma_f32_32x32x16_bf16 v[18:33], v[210:213], v[2:5], v[18:33]
	ds_read_b128 v[236:239], v248 offset:50784
	v_mfma_f32_32x32x16_bf16 v[34:49], v[214:217], v[2:5], v[34:49]
	global_load_dwordx4 v[158:161], v227, s[80:81] offset:1536
	s_waitcnt lgkmcnt(6)
	v_mfma_f32_32x32x16_bf16 v[114:129], v[228:231], v[6:9], v[114:129]
	s_waitcnt vmcnt(15)
	ds_write_b128 v251, v[190:193] offset:27648
	s_waitcnt lgkmcnt(6)
	v_mfma_f32_32x32x16_bf16 v[130:145], v[232:235], v[6:9], v[130:145]
	s_waitcnt lgkmcnt(4)
	v_mfma_f32_32x32x16_bf16 v[82:97], v[228:231], v[10:13], v[82:97]
	global_load_dwordx4 v[190:193], v227, s[92:93] offset:1536
	v_mfma_f32_32x32x16_bf16 v[98:113], v[232:235], v[10:13], v[98:113]
	s_waitcnt lgkmcnt(3)
	v_mfma_f32_32x32x16_bf16 v[50:65], v[228:231], v[14:17], v[50:65]
	v_mfma_f32_32x32x16_bf16 v[66:81], v[232:235], v[14:17], v[66:81]
	s_waitcnt lgkmcnt(1)
	v_mfma_f32_32x32x16_bf16 v[18:33], v[228:231], v[236:239], v[18:33]
	v_mfma_f32_32x32x16_bf16 v[34:49], v[232:235], v[236:239], v[34:49]
	s_waitcnt lgkmcnt(0)
	s_barrier
;     ...
;   for (int kt = 0; kt < nk; ++kt) {
;     __syncthreads();
;     if (kt + 1 < nk) {
;       u16* aw = As0 + ((kt + 1) & 1) * 256 * LD;
;       u16* bw = Bs0 + ((kt + 1) & 1) * 256 * LD;
; #pragma unroll
;       for (int i = 0; i < 4; ++i) { *(u32x4*)(aw + (srow + 64 * i) * LD + skc * 8) = ra[i]; *(u32x4*)(bw + (srow + 64 * i) * LD + skc * 8) = rb[i]; }
;     }
;     if (kt + 2 < nk) {
; #pragma unroll
;       for (int i = 0; i < 4; ++i) { ra[i] = *(const u32x4*)(Ag + (size_t)(64 * i) * K + (kt + 2) * 64); rb[i] = *(const u32x4*)(Bg[i] + (kt + 2) * 64); }
;     }
;     __builtin_amdgcn_sched_barrier(0);
;     const u16* as = As0 + (kt & 1) * 256 * LD + (wr * 128 + l31) * LD + h * 8;
;     const u16* bs = Bs0 + (kt & 1) * 256 * LD + (wc * 64 + l31) * LD + h * 8;
;     if (domma)
; #pragma unroll
;     for (int ks = 0; ks < 4; ++ks) {
;       bf16x8 wf[2], xf[4];
; #pragma unroll
;       for (int ct = 0; ct < 2; ++ct) wf[ct] = *(const bf16x8*)(bs + ct * 32 * LD + ks * 16);
; #pragma unroll
;       for (int tt = 0; tt < 4; ++tt) xf[tt] = *(const bf16x8*)(as + tt * 32 * LD + ks * 16);
; #pragma unroll
;       for (int ct = 0; ct < 2; ++ct)
; #pragma unroll
;         for (int tt = 0; tt < 4; ++tt) acc[ct][tt] = __builtin_amdgcn_mfma_f32_32x32x16_bf16(wf[ct], xf[tt], acc[ct][tt], 0, 0, 0);
;     }
	ds_read_b128 v[210:213], v249
	ds_read_b128 v[236:239], v248
	ds_read_b128 v[214:217], v249 offset:4608
	ds_read_b128 v[2:5], v248 offset:4608
	ds_read_b128 v[6:9], v248 offset:9216
	ds_read_b128 v[10:13], v248 offset:13824
	s_waitcnt lgkmcnt(4)
	v_mfma_f32_32x32x16_bf16 v[114:129], v[210:213], v[236:239], v[114:129]
	ds_read_b128 v[228:231], v249 offset:32
	s_waitcnt lgkmcnt(4)
	v_mfma_f32_32x32x16_bf16 v[130:145], v[214:217], v[236:239], v[130:145]
	ds_read_b128 v[14:17], v248 offset:32
	s_waitcnt lgkmcnt(4)
	v_mfma_f32_32x32x16_bf16 v[82:97], v[210:213], v[2:5], v[82:97]
	ds_read_b128 v[232:235], v249 offset:4640
	v_mfma_f32_32x32x16_bf16 v[98:113], v[214:217], v[2:5], v[98:113]
	ds_read_b128 v[236:239], v248 offset:4640
	s_waitcnt vmcnt(15)
	ds_write_b128 v250, v[162:165] offset:36864
	s_waitcnt lgkmcnt(6)
	v_mfma_f32_32x32x16_bf16 v[50:65], v[210:213], v[6:9], v[50:65]
	ds_read_b128 v[2:5], v248 offset:9248
	v_mfma_f32_32x32x16_bf16 v[66:81], v[214:217], v[6:9], v[66:81]
	global_load_dwordx4 v[162:165], v227, s[74:75] offset:1664
	s_waitcnt lgkmcnt(6)
	v_mfma_f32_32x32x16_bf16 v[18:33], v[210:213], v[10:13], v[18:33]
	ds_read_b128 v[6:9], v248 offset:13856
	s_waitcnt vmcnt(15)
	ds_write_b128 v251, v[194:197] offset:36864
	v_mfma_f32_32x32x16_bf16 v[34:49], v[214:217], v[10:13], v[34:49]
	s_waitcnt lgkmcnt(6)
	v_mfma_f32_32x32x16_bf16 v[114:129], v[228:231], v[14:17], v[114:129]
	ds_read_b128 v[210:213], v249 offset:64
	global_load_dwordx4 v[194:197], v227, s[82:83] offset:1664
	s_waitcnt lgkmcnt(6)
	v_mfma_f32_32x32x16_bf16 v[130:145], v[232:235], v[14:17], v[130:145]
	ds_read_b128 v[10:13], v248 offset:64
	s_waitcnt vmcnt(15)
	ds_write_b128 v250, v[166:169] offset:46080
	s_waitcnt lgkmcnt(7)
	v_mfma_f32_32x32x16_bf16 v[82:97], v[228:231], v[236:239], v[82:97]
	ds_read_b128 v[214:217], v249 offset:4672
	v_mfma_f32_32x32x16_bf16 v[98:113], v[232:235], v[236:239], v[98:113]
	ds_read_b128 v[14:17], v248 offset:4672
	global_load_dwordx4 v[166:169], v227, s[76:77] offset:1664
	s_waitcnt lgkmcnt(7)
	v_mfma_f32_32x32x16_bf16 v[50:65], v[228:231], v[2:5], v[50:65]
	ds_read_b128 v[236:239], v248 offset:9280
	s_waitcnt vmcnt(15)
	ds_write_b128 v251, v[198:201] offset:46080
	v_mfma_f32_32x32x16_bf16 v[66:81], v[232:235], v[2:5], v[66:81]
	s_waitcnt lgkmcnt(8)
	v_mfma_f32_32x32x16_bf16 v[18:33], v[228:231], v[6:9], v[18:33]
	ds_read_b128 v[2:5], v248 offset:13888
	global_load_dwordx4 v[198:201], v227, s[84:85] offset:1664
	v_mfma_f32_32x32x16_bf16 v[34:49], v[232:235], v[6:9], v[34:49]
	s_waitcnt vmcnt(15)
	ds_write_b128 v250, v[170:173] offset:55296
	s_waitcnt lgkmcnt(7)
	v_mfma_f32_32x32x16_bf16 v[114:129], v[210:213], v[10:13], v[114:129]
	ds_read_b128 v[228:231], v249 offset:96
	s_waitcnt lgkmcnt(6)
	v_mfma_f32_32x32x16_bf16 v[130:145], v[214:217], v[10:13], v[130:145]
	ds_read_b128 v[6:9], v248 offset:96
	global_load_dwordx4 v[170:173], v227, s[78:79] offset:1664
	s_waitcnt lgkmcnt(6)
	v_mfma_f32_32x32x16_bf16 v[82:97], v[210:213], v[14:17], v[82:97]
	ds_read_b128 v[232:235], v249 offset:4704
	s_waitcnt vmcnt(15)
	ds_write_b128 v251, v[202:205] offset:55296
	v_mfma_f32_32x32x16_bf16 v[98:113], v[214:217], v[14:17], v[98:113]
	ds_read_b128 v[10:13], v248 offset:4704
	s_waitcnt lgkmcnt(8)
	v_mfma_f32_32x32x16_bf16 v[50:65], v[210:213], v[236:239], v[50:65]
	ds_read_b128 v[14:17], v248 offset:9312
	global_load_dwordx4 v[202:205], v227, s[86:87] offset:1664
	v_mfma_f32_32x32x16_bf16 v[66:81], v[214:217], v[236:239], v[66:81]
	s_waitcnt vmcnt(15)
	ds_write_b128 v250, v[174:177] offset:64512
	s_waitcnt lgkmcnt(8)
	v_mfma_f32_32x32x16_bf16 v[18:33], v[210:213], v[2:5], v[18:33]
	ds_read_b128 v[236:239], v248 offset:13920
	v_mfma_f32_32x32x16_bf16 v[34:49], v[214:217], v[2:5], v[34:49]
	global_load_dwordx4 v[174:177], v227, s[80:81] offset:1664
	s_waitcnt lgkmcnt(6)
	v_mfma_f32_32x32x16_bf16 v[114:129], v[228:231], v[6:9], v[114:129]
	s_waitcnt vmcnt(15)
	ds_write_b128 v251, v[206:209] offset:64512
	s_waitcnt lgkmcnt(6)
	v_mfma_f32_32x32x16_bf16 v[130:145], v[232:235], v[6:9], v[130:145]
	s_waitcnt lgkmcnt(4)
	v_mfma_f32_32x32x16_bf16 v[82:97], v[228:231], v[10:13], v[82:97]
	global_load_dwordx4 v[206:209], v227, s[92:93] offset:1664
	v_mfma_f32_32x32x16_bf16 v[98:113], v[232:235], v[10:13], v[98:113]
	s_waitcnt lgkmcnt(3)
	v_mfma_f32_32x32x16_bf16 v[50:65], v[228:231], v[14:17], v[50:65]
	v_mfma_f32_32x32x16_bf16 v[66:81], v[232:235], v[14:17], v[66:81]
	s_waitcnt lgkmcnt(1)
	v_mfma_f32_32x32x16_bf16 v[18:33], v[228:231], v[236:239], v[18:33]
	v_mfma_f32_32x32x16_bf16 v[34:49], v[232:235], v[236:239], v[34:49]
	s_waitcnt lgkmcnt(0)
	s_barrier
;     ...
;   for (int kt = 0; kt < nk; ++kt) {
;     __syncthreads();
;     if (kt + 1 < nk) {
;       u16* aw = As0 + ((kt + 1) & 1) * 256 * LD;
;       u16* bw = Bs0 + ((kt + 1) & 1) * 256 * LD;
; #pragma unroll
;       for (int i = 0; i < 4; ++i) { *(u32x4*)(aw + (srow + 64 * i) * LD + skc * 8) = ra[i]; *(u32x4*)(bw + (srow + 64 * i) * LD + skc * 8) = rb[i]; }
;     }
;     if (kt + 2 < nk) {
; #pragma unroll
;       for (int i = 0; i < 4; ++i) { ra[i] = *(const u32x4*)(Ag + (size_t)(64 * i) * K + (kt + 2) * 64); rb[i] = *(const u32x4*)(Bg[i] + (kt + 2) * 64); }
;     }
;     __builtin_amdgcn_sched_barrier(0);
;     const u16* as = As0 + (kt & 1) * 256 * LD + (wr * 128 + l31) * LD + h * 8;
;     const u16* bs = Bs0 + (kt & 1) * 256 * LD + (wc * 64 + l31) * LD + h * 8;
;     if (domma)
; #pragma unroll
;     for (int ks = 0; ks < 4; ++ks) {
;       bf16x8 wf[2], xf[4];
; #pragma unroll
;       for (int ct = 0; ct < 2; ++ct) wf[ct] = *(const bf16x8*)(bs + ct * 32 * LD + ks * 16);
; #pragma unroll
;       for (int tt = 0; tt < 4; ++tt) xf[tt] = *(const bf16x8*)(as + tt * 32 * LD + ks * 16);
; #pragma unroll
;       for (int ct = 0; ct < 2; ++ct)
; #pragma unroll
;         for (int tt = 0; tt < 4; ++tt) acc[ct][tt] = __builtin_amdgcn_mfma_f32_32x32x16_bf16(wf[ct], xf[tt], acc[ct][tt], 0, 0, 0);
;     }
	ds_read_b128 v[210:213], v249 offset:36864
	ds_read_b128 v[236:239], v248 offset:36864
	ds_read_b128 v[214:217], v249 offset:41472
	ds_read_b128 v[2:5], v248 offset:41472
	ds_read_b128 v[6:9], v248 offset:46080
	ds_read_b128 v[10:13], v248 offset:50688
	s_waitcnt lgkmcnt(4)
	v_mfma_f32_32x32x16_bf16 v[114:129], v[210:213], v[236:239], v[114:129]
	ds_read_b128 v[228:231], v249 offset:36896
	s_waitcnt lgkmcnt(4)
	v_mfma_f32_32x32x16_bf16 v[130:145], v[214:217], v[236:239], v[130:145]
	ds_read_b128 v[14:17], v248 offset:36896
	s_waitcnt lgkmcnt(4)
	v_mfma_f32_32x32x16_bf16 v[82:97], v[210:213], v[2:5], v[82:97]
	ds_read_b128 v[232:235], v249 offset:41504
	v_mfma_f32_32x32x16_bf16 v[98:113], v[214:217], v[2:5], v[98:113]
	ds_read_b128 v[236:239], v248 offset:41504
	s_waitcnt vmcnt(15)
	ds_write_b128 v250, v[146:149]
	s_waitcnt lgkmcnt(6)
	v_mfma_f32_32x32x16_bf16 v[50:65], v[210:213], v[6:9], v[50:65]
	ds_read_b128 v[2:5], v248 offset:46112
	v_mfma_f32_32x32x16_bf16 v[66:81], v[214:217], v[6:9], v[66:81]
	global_load_dwordx4 v[146:149], v227, s[74:75] offset:1792
	s_waitcnt lgkmcnt(6)
	v_mfma_f32_32x32x16_bf16 v[18:33], v[210:213], v[10:13], v[18:33]
	ds_read_b128 v[6:9], v248 offset:50720
	s_waitcnt vmcnt(15)
	ds_write_b128 v251, v[178:181]
	v_mfma_f32_32x32x16_bf16 v[34:49], v[214:217], v[10:13], v[34:49]
	s_waitcnt lgkmcnt(6)
	v_mfma_f32_32x32x16_bf16 v[114:129], v[228:231], v[14:17], v[114:129]
	ds_read_b128 v[210:213], v249 offset:36928
	global_load_dwordx4 v[178:181], v227, s[82:83] offset:1792
	s_waitcnt lgkmcnt(6)
	v_mfma_f32_32x32x16_bf16 v[130:145], v[232:235], v[14:17], v[130:145]
	ds_read_b128 v[10:13], v248 offset:36928
	s_waitcnt vmcnt(15)
	ds_write_b128 v250, v[150:153] offset:9216
	s_waitcnt lgkmcnt(7)
	v_mfma_f32_32x32x16_bf16 v[82:97], v[228:231], v[236:239], v[82:97]
	ds_read_b128 v[214:217], v249 offset:41536
	v_mfma_f32_32x32x16_bf16 v[98:113], v[232:235], v[236:239], v[98:113]
	ds_read_b128 v[14:17], v248 offset:41536
	global_load_dwordx4 v[150:153], v227, s[76:77] offset:1792
	s_waitcnt lgkmcnt(7)
	v_mfma_f32_32x32x16_bf16 v[50:65], v[228:231], v[2:5], v[50:65]
	ds_read_b128 v[236:239], v248 offset:46144
	s_waitcnt vmcnt(15)
	ds_write_b128 v251, v[182:185] offset:9216
	v_mfma_f32_32x32x16_bf16 v[66:81], v[232:235], v[2:5], v[66:81]
	s_waitcnt lgkmcnt(8)
	v_mfma_f32_32x32x16_bf16 v[18:33], v[228:231], v[6:9], v[18:33]
	ds_read_b128 v[2:5], v248 offset:50752
	global_load_dwordx4 v[182:185], v227, s[84:85] offset:1792
	v_mfma_f32_32x32x16_bf16 v[34:49], v[232:235], v[6:9], v[34:49]
	s_waitcnt vmcnt(15)
	ds_write_b128 v250, v[154:157] offset:18432
	s_waitcnt lgkmcnt(7)
	v_mfma_f32_32x32x16_bf16 v[114:129], v[210:213], v[10:13], v[114:129]
	ds_read_b128 v[228:231], v249 offset:36960
	s_waitcnt lgkmcnt(6)
	v_mfma_f32_32x32x16_bf16 v[130:145], v[214:217], v[10:13], v[130:145]
	ds_read_b128 v[6:9], v248 offset:36960
	global_load_dwordx4 v[154:157], v227, s[78:79] offset:1792
	s_waitcnt lgkmcnt(6)
	v_mfma_f32_32x32x16_bf16 v[82:97], v[210:213], v[14:17], v[82:97]
	ds_read_b128 v[232:235], v249 offset:41568
	s_waitcnt vmcnt(15)
	ds_write_b128 v251, v[186:189] offset:18432
	v_mfma_f32_32x32x16_bf16 v[98:113], v[214:217], v[14:17], v[98:113]
	ds_read_b128 v[10:13], v248 offset:41568
	s_waitcnt lgkmcnt(8)
	v_mfma_f32_32x32x16_bf16 v[50:65], v[210:213], v[236:239], v[50:65]
	ds_read_b128 v[14:17], v248 offset:46176
	global_load_dwordx4 v[186:189], v227, s[86:87] offset:1792
	v_mfma_f32_32x32x16_bf16 v[66:81], v[214:217], v[236:239], v[66:81]
	s_waitcnt vmcnt(15)
	ds_write_b128 v250, v[158:161] offset:27648
	s_waitcnt lgkmcnt(8)
	v_mfma_f32_32x32x16_bf16 v[18:33], v[210:213], v[2:5], v[18:33]
	ds_read_b128 v[236:239], v248 offset:50784
	v_mfma_f32_32x32x16_bf16 v[34:49], v[214:217], v[2:5], v[34:49]
	global_load_dwordx4 v[158:161], v227, s[80:81] offset:1792
	s_waitcnt lgkmcnt(6)
	v_mfma_f32_32x32x16_bf16 v[114:129], v[228:231], v[6:9], v[114:129]
	s_waitcnt vmcnt(15)
	ds_write_b128 v251, v[190:193] offset:27648
	s_waitcnt lgkmcnt(6)
	v_mfma_f32_32x32x16_bf16 v[130:145], v[232:235], v[6:9], v[130:145]
	s_waitcnt lgkmcnt(4)
	v_mfma_f32_32x32x16_bf16 v[82:97], v[228:231], v[10:13], v[82:97]
	global_load_dwordx4 v[190:193], v227, s[92:93] offset:1792
	v_mfma_f32_32x32x16_bf16 v[98:113], v[232:235], v[10:13], v[98:113]
	s_waitcnt lgkmcnt(3)
	v_mfma_f32_32x32x16_bf16 v[50:65], v[228:231], v[14:17], v[50:65]
	v_mfma_f32_32x32x16_bf16 v[66:81], v[232:235], v[14:17], v[66:81]
	s_waitcnt lgkmcnt(1)
	v_mfma_f32_32x32x16_bf16 v[18:33], v[228:231], v[236:239], v[18:33]
	v_mfma_f32_32x32x16_bf16 v[34:49], v[232:235], v[236:239], v[34:49]
	s_waitcnt lgkmcnt(0)
	s_barrier
;     ...
;   for (int kt = 0; kt < nk; ++kt) {
;     __syncthreads();
;     if (kt + 1 < nk) {
;       u16* aw = As0 + ((kt + 1) & 1) * 256 * LD;
;       u16* bw = Bs0 + ((kt + 1) & 1) * 256 * LD;
; #pragma unroll
;       for (int i = 0; i < 4; ++i) { *(u32x4*)(aw + (srow + 64 * i) * LD + skc * 8) = ra[i]; *(u32x4*)(bw + (srow + 64 * i) * LD + skc * 8) = rb[i]; }
;     }
;     if (kt + 2 < nk) {
; #pragma unroll
;       for (int i = 0; i < 4; ++i) { ra[i] = *(const u32x4*)(Ag + (size_t)(64 * i) * K + (kt + 2) * 64); rb[i] = *(const u32x4*)(Bg[i] + (kt + 2) * 64); }
;     }
;     __builtin_amdgcn_sched_barrier(0);
;     const u16* as = As0 + (kt & 1) * 256 * LD + (wr * 128 + l31) * LD + h * 8;
;     const u16* bs = Bs0 + (kt & 1) * 256 * LD + (wc * 64 + l31) * LD + h * 8;
;     if (domma)
; #pragma unroll
;     for (int ks = 0; ks < 4; ++ks) {
;       bf16x8 wf[2], xf[4];
; #pragma unroll
;       for (int ct = 0; ct < 2; ++ct) wf[ct] = *(const bf16x8*)(bs + ct * 32 * LD + ks * 16);
; #pragma unroll
;       for (int tt = 0; tt < 4; ++tt) xf[tt] = *(const bf16x8*)(as + tt * 32 * LD + ks * 16);
; #pragma unroll
;       for (int ct = 0; ct < 2; ++ct)
; #pragma unroll
;         for (int tt = 0; tt < 4; ++tt) acc[ct][tt] = __builtin_amdgcn_mfma_f32_32x32x16_bf16(wf[ct], xf[tt], acc[ct][tt], 0, 0, 0);
;     }
	ds_read_b128 v[210:213], v249
	ds_read_b128 v[236:239], v248
	ds_read_b128 v[214:217], v249 offset:4608
	ds_read_b128 v[2:5], v248 offset:4608
	ds_read_b128 v[6:9], v248 offset:9216
	ds_read_b128 v[10:13], v248 offset:13824
	s_waitcnt lgkmcnt(4)
	v_mfma_f32_32x32x16_bf16 v[114:129], v[210:213], v[236:239], v[114:129]
	ds_read_b128 v[228:231], v249 offset:32
	s_waitcnt lgkmcnt(4)
	v_mfma_f32_32x32x16_bf16 v[130:145], v[214:217], v[236:239], v[130:145]
	ds_read_b128 v[14:17], v248 offset:32
	s_waitcnt lgkmcnt(4)
	v_mfma_f32_32x32x16_bf16 v[82:97], v[210:213], v[2:5], v[82:97]
	ds_read_b128 v[232:235], v249 offset:4640
	v_mfma_f32_32x32x16_bf16 v[98:113], v[214:217], v[2:5], v[98:113]
	ds_read_b128 v[236:239], v248 offset:4640
	s_waitcnt vmcnt(15)
	ds_write_b128 v250, v[162:165] offset:36864
	s_waitcnt lgkmcnt(6)
	v_mfma_f32_32x32x16_bf16 v[50:65], v[210:213], v[6:9], v[50:65]
	ds_read_b128 v[2:5], v248 offset:9248
	v_mfma_f32_32x32x16_bf16 v[66:81], v[214:217], v[6:9], v[66:81]
	global_load_dwordx4 v[162:165], v227, s[74:75] offset:1920
	s_waitcnt lgkmcnt(6)
	v_mfma_f32_32x32x16_bf16 v[18:33], v[210:213], v[10:13], v[18:33]
	ds_read_b128 v[6:9], v248 offset:13856
	s_waitcnt vmcnt(15)
	ds_write_b128 v251, v[194:197] offset:36864
	v_mfma_f32_32x32x16_bf16 v[34:49], v[214:217], v[10:13], v[34:49]
	s_waitcnt lgkmcnt(6)
	v_mfma_f32_32x32x16_bf16 v[114:129], v[228:231], v[14:17], v[114:129]
	ds_read_b128 v[210:213], v249 offset:64
	global_load_dwordx4 v[194:197], v227, s[82:83] offset:1920
	s_waitcnt lgkmcnt(6)
	v_mfma_f32_32x32x16_bf16 v[130:145], v[232:235], v[14:17], v[130:145]
	ds_read_b128 v[10:13], v248 offset:64
	s_waitcnt vmcnt(15)
	ds_write_b128 v250, v[166:169] offset:46080
	s_waitcnt lgkmcnt(7)
	v_mfma_f32_32x32x16_bf16 v[82:97], v[228:231], v[236:239], v[82:97]
	ds_read_b128 v[214:217], v249 offset:4672
	v_mfma_f32_32x32x16_bf16 v[98:113], v[232:235], v[236:239], v[98:113]
	ds_read_b128 v[14:17], v248 offset:4672
	global_load_dwordx4 v[166:169], v227, s[76:77] offset:1920
	s_waitcnt lgkmcnt(7)
	v_mfma_f32_32x32x16_bf16 v[50:65], v[228:231], v[2:5], v[50:65]
	ds_read_b128 v[236:239], v248 offset:9280
	s_waitcnt vmcnt(15)
	ds_write_b128 v251, v[198:201] offset:46080
	v_mfma_f32_32x32x16_bf16 v[66:81], v[232:235], v[2:5], v[66:81]
	s_waitcnt lgkmcnt(8)
	v_mfma_f32_32x32x16_bf16 v[18:33], v[228:231], v[6:9], v[18:33]
	ds_read_b128 v[2:5], v248 offset:13888
	global_load_dwordx4 v[198:201], v227, s[84:85] offset:1920
	v_mfma_f32_32x32x16_bf16 v[34:49], v[232:235], v[6:9], v[34:49]
	s_waitcnt vmcnt(15)
	ds_write_b128 v250, v[170:173] offset:55296
	s_waitcnt lgkmcnt(7)
	v_mfma_f32_32x32x16_bf16 v[114:129], v[210:213], v[10:13], v[114:129]
	ds_read_b128 v[228:231], v249 offset:96
	s_waitcnt lgkmcnt(6)
	v_mfma_f32_32x32x16_bf16 v[130:145], v[214:217], v[10:13], v[130:145]
	ds_read_b128 v[6:9], v248 offset:96
	global_load_dwordx4 v[170:173], v227, s[78:79] offset:1920
	s_waitcnt lgkmcnt(6)
	v_mfma_f32_32x32x16_bf16 v[82:97], v[210:213], v[14:17], v[82:97]
	ds_read_b128 v[232:235], v249 offset:4704
	s_waitcnt vmcnt(15)
	ds_write_b128 v251, v[202:205] offset:55296
	v_mfma_f32_32x32x16_bf16 v[98:113], v[214:217], v[14:17], v[98:113]
	ds_read_b128 v[10:13], v248 offset:4704
	s_waitcnt lgkmcnt(8)
	v_mfma_f32_32x32x16_bf16 v[50:65], v[210:213], v[236:239], v[50:65]
	ds_read_b128 v[14:17], v248 offset:9312
	global_load_dwordx4 v[202:205], v227, s[86:87] offset:1920
	v_mfma_f32_32x32x16_bf16 v[66:81], v[214:217], v[236:239], v[66:81]
	s_waitcnt vmcnt(15)
	ds_write_b128 v250, v[174:177] offset:64512
	s_waitcnt lgkmcnt(8)
	v_mfma_f32_32x32x16_bf16 v[18:33], v[210:213], v[2:5], v[18:33]
	ds_read_b128 v[236:239], v248 offset:13920
	v_mfma_f32_32x32x16_bf16 v[34:49], v[214:217], v[2:5], v[34:49]
	global_load_dwordx4 v[174:177], v227, s[80:81] offset:1920
	s_waitcnt lgkmcnt(6)
	v_mfma_f32_32x32x16_bf16 v[114:129], v[228:231], v[6:9], v[114:129]
	s_waitcnt vmcnt(15)
	ds_write_b128 v251, v[206:209] offset:64512
	s_waitcnt lgkmcnt(6)
	v_mfma_f32_32x32x16_bf16 v[130:145], v[232:235], v[6:9], v[130:145]
	s_waitcnt lgkmcnt(4)
	v_mfma_f32_32x32x16_bf16 v[82:97], v[228:231], v[10:13], v[82:97]
	global_load_dwordx4 v[206:209], v227, s[92:93] offset:1920
	v_mfma_f32_32x32x16_bf16 v[98:113], v[232:235], v[10:13], v[98:113]
	s_waitcnt lgkmcnt(3)
	v_mfma_f32_32x32x16_bf16 v[50:65], v[228:231], v[14:17], v[50:65]
	v_mfma_f32_32x32x16_bf16 v[66:81], v[232:235], v[14:17], v[66:81]
	s_waitcnt lgkmcnt(1)
	v_mfma_f32_32x32x16_bf16 v[18:33], v[228:231], v[236:239], v[18:33]
	v_mfma_f32_32x32x16_bf16 v[34:49], v[232:235], v[236:239], v[34:49]
	s_waitcnt lgkmcnt(0)
	s_barrier
;     ...
;   for (int kt = 0; kt < nk; ++kt) {
;     __syncthreads();
;     if (kt + 1 < nk) {
;       u16* aw = As0 + ((kt + 1) & 1) * 256 * LD;
;       u16* bw = Bs0 + ((kt + 1) & 1) * 256 * LD;
; #pragma unroll
;       for (int i = 0; i < 4; ++i) { *(u32x4*)(aw + (srow + 64 * i) * LD + skc * 8) = ra[i]; *(u32x4*)(bw + (srow + 64 * i) * LD + skc * 8) = rb[i]; }
;     }
;     if (kt + 2 < nk) {
; #pragma unroll
;       for (int i = 0; i < 4; ++i) { ra[i] = *(const u32x4*)(Ag + (size_t)(64 * i) * K + (kt + 2) * 64); rb[i] = *(const u32x4*)(Bg[i] + (kt + 2) * 64); }
;     }
;     __builtin_amdgcn_sched_barrier(0);
;     const u16* as = As0 + (kt & 1) * 256 * LD + (wr * 128 + l31) * LD + h * 8;
;     const u16* bs = Bs0 + (kt & 1) * 256 * LD + (wc * 64 + l31) * LD + h * 8;
;     if (domma)
; #pragma unroll
;     for (int ks = 0; ks < 4; ++ks) {
;       bf16x8 wf[2], xf[4];
; #pragma unroll
;       for (int ct = 0; ct < 2; ++ct) wf[ct] = *(const bf16x8*)(bs + ct * 32 * LD + ks * 16);
; #pragma unroll
;       for (int tt = 0; tt < 4; ++tt) xf[tt] = *(const bf16x8*)(as + tt * 32 * LD + ks * 16);
; #pragma unroll
;       for (int ct = 0; ct < 2; ++ct)
; #pragma unroll
;         for (int tt = 0; tt < 4; ++tt) acc[ct][tt] = __builtin_amdgcn_mfma_f32_32x32x16_bf16(wf[ct], xf[tt], acc[ct][tt], 0, 0, 0);
;     }
;     __builtin_amdgcn_sched_barrier(0);
;   }
	ds_read_b128 v[210:213], v249 offset:36864
	ds_read_b128 v[236:239], v248 offset:36864
	ds_read_b128 v[214:217], v249 offset:41472
	ds_read_b128 v[2:5], v248 offset:41472
	ds_read_b128 v[6:9], v248 offset:46080
	ds_read_b128 v[10:13], v248 offset:50688
	s_waitcnt lgkmcnt(4)
	v_mfma_f32_32x32x16_bf16 v[114:129], v[210:213], v[236:239], v[114:129]
	ds_read_b128 v[228:231], v249 offset:36896
	s_waitcnt lgkmcnt(4)
	v_mfma_f32_32x32x16_bf16 v[130:145], v[214:217], v[236:239], v[130:145]
	ds_read_b128 v[14:17], v248 offset:36896
	s_waitcnt lgkmcnt(4)
	v_mfma_f32_32x32x16_bf16 v[82:97], v[210:213], v[2:5], v[82:97]
	ds_read_b128 v[232:235], v249 offset:41504
	v_mfma_f32_32x32x16_bf16 v[98:113], v[214:217], v[2:5], v[98:113]
	ds_read_b128 v[236:239], v248 offset:41504
	s_waitcnt vmcnt(15)
	ds_write_b128 v250, v[146:149]
	s_waitcnt lgkmcnt(6)
	v_mfma_f32_32x32x16_bf16 v[50:65], v[210:213], v[6:9], v[50:65]
	ds_read_b128 v[2:5], v248 offset:46112
	v_mfma_f32_32x32x16_bf16 v[66:81], v[214:217], v[6:9], v[66:81]
	s_waitcnt lgkmcnt(6)
	v_mfma_f32_32x32x16_bf16 v[18:33], v[210:213], v[10:13], v[18:33]
	ds_read_b128 v[6:9], v248 offset:50720
	s_waitcnt vmcnt(14)
	ds_write_b128 v251, v[178:181]
	v_mfma_f32_32x32x16_bf16 v[34:49], v[214:217], v[10:13], v[34:49]
	s_waitcnt lgkmcnt(6)
	v_mfma_f32_32x32x16_bf16 v[114:129], v[228:231], v[14:17], v[114:129]
	ds_read_b128 v[210:213], v249 offset:36928
	s_waitcnt lgkmcnt(6)
	v_mfma_f32_32x32x16_bf16 v[130:145], v[232:235], v[14:17], v[130:145]
	ds_read_b128 v[10:13], v248 offset:36928
	s_waitcnt vmcnt(13)
	ds_write_b128 v250, v[150:153] offset:9216
	s_waitcnt lgkmcnt(7)
	v_mfma_f32_32x32x16_bf16 v[82:97], v[228:231], v[236:239], v[82:97]
	ds_read_b128 v[214:217], v249 offset:41536
	v_mfma_f32_32x32x16_bf16 v[98:113], v[232:235], v[236:239], v[98:113]
	ds_read_b128 v[14:17], v248 offset:41536
	s_waitcnt lgkmcnt(7)
	v_mfma_f32_32x32x16_bf16 v[50:65], v[228:231], v[2:5], v[50:65]
	ds_read_b128 v[236:239], v248 offset:46144
	s_waitcnt vmcnt(12)
	ds_write_b128 v251, v[182:185] offset:9216
	v_mfma_f32_32x32x16_bf16 v[66:81], v[232:235], v[2:5], v[66:81]
	s_waitcnt lgkmcnt(8)
	v_mfma_f32_32x32x16_bf16 v[18:33], v[228:231], v[6:9], v[18:33]
	ds_read_b128 v[2:5], v248 offset:50752
	v_mfma_f32_32x32x16_bf16 v[34:49], v[232:235], v[6:9], v[34:49]
	s_waitcnt vmcnt(11)
	ds_write_b128 v250, v[154:157] offset:18432
	s_waitcnt lgkmcnt(7)
	v_mfma_f32_32x32x16_bf16 v[114:129], v[210:213], v[10:13], v[114:129]
	ds_read_b128 v[228:231], v249 offset:36960
	s_waitcnt lgkmcnt(6)
	v_mfma_f32_32x32x16_bf16 v[130:145], v[214:217], v[10:13], v[130:145]
	ds_read_b128 v[6:9], v248 offset:36960
	s_waitcnt lgkmcnt(6)
	v_mfma_f32_32x32x16_bf16 v[82:97], v[210:213], v[14:17], v[82:97]
	ds_read_b128 v[232:235], v249 offset:41568
	s_waitcnt vmcnt(10)
	ds_write_b128 v251, v[186:189] offset:18432
	v_mfma_f32_32x32x16_bf16 v[98:113], v[214:217], v[14:17], v[98:113]
	ds_read_b128 v[10:13], v248 offset:41568
	s_waitcnt lgkmcnt(8)
	v_mfma_f32_32x32x16_bf16 v[50:65], v[210:213], v[236:239], v[50:65]
	ds_read_b128 v[14:17], v248 offset:46176
	v_mfma_f32_32x32x16_bf16 v[66:81], v[214:217], v[236:239], v[66:81]
	s_waitcnt vmcnt(9)
	ds_write_b128 v250, v[158:161] offset:27648
	s_waitcnt lgkmcnt(8)
	v_mfma_f32_32x32x16_bf16 v[18:33], v[210:213], v[2:5], v[18:33]
	ds_read_b128 v[236:239], v248 offset:50784
	v_mfma_f32_32x32x16_bf16 v[34:49], v[214:217], v[2:5], v[34:49]
	s_waitcnt lgkmcnt(6)
	v_mfma_f32_32x32x16_bf16 v[114:129], v[228:231], v[6:9], v[114:129]
	s_waitcnt vmcnt(8)
	ds_write_b128 v251, v[190:193] offset:27648
	s_waitcnt lgkmcnt(6)
	v_mfma_f32_32x32x16_bf16 v[130:145], v[232:235], v[6:9], v[130:145]
	s_waitcnt lgkmcnt(4)
	v_mfma_f32_32x32x16_bf16 v[82:97], v[228:231], v[10:13], v[82:97]
	v_mfma_f32_32x32x16_bf16 v[98:113], v[232:235], v[10:13], v[98:113]
	s_waitcnt lgkmcnt(3)
	v_mfma_f32_32x32x16_bf16 v[50:65], v[228:231], v[14:17], v[50:65]
	v_mfma_f32_32x32x16_bf16 v[66:81], v[232:235], v[14:17], v[66:81]
	s_waitcnt lgkmcnt(1)
	v_mfma_f32_32x32x16_bf16 v[18:33], v[228:231], v[236:239], v[18:33]
	v_mfma_f32_32x32x16_bf16 v[34:49], v[232:235], v[236:239], v[34:49]
	s_waitcnt lgkmcnt(0)
	s_barrier
	ds_read_b128 v[210:213], v249
	ds_read_b128 v[236:239], v248
	ds_read_b128 v[214:217], v249 offset:4608
	ds_read_b128 v[2:5], v248 offset:4608
	ds_read_b128 v[6:9], v248 offset:9216
	ds_read_b128 v[10:13], v248 offset:13824
	s_waitcnt lgkmcnt(4)
	v_mfma_f32_32x32x16_bf16 v[114:129], v[210:213], v[236:239], v[114:129]
	ds_read_b128 v[228:231], v249 offset:32
	s_waitcnt lgkmcnt(4)
	v_mfma_f32_32x32x16_bf16 v[130:145], v[214:217], v[236:239], v[130:145]
	ds_read_b128 v[14:17], v248 offset:32
	s_waitcnt lgkmcnt(4)
	v_mfma_f32_32x32x16_bf16 v[82:97], v[210:213], v[2:5], v[82:97]
	ds_read_b128 v[232:235], v249 offset:4640
	v_mfma_f32_32x32x16_bf16 v[98:113], v[214:217], v[2:5], v[98:113]
	ds_read_b128 v[236:239], v248 offset:4640
	s_waitcnt vmcnt(7)
	ds_write_b128 v250, v[162:165] offset:36864
	s_waitcnt lgkmcnt(6)
	v_mfma_f32_32x32x16_bf16 v[50:65], v[210:213], v[6:9], v[50:65]
	ds_read_b128 v[2:5], v248 offset:9248
	v_mfma_f32_32x32x16_bf16 v[66:81], v[214:217], v[6:9], v[66:81]
	s_waitcnt lgkmcnt(6)
	v_mfma_f32_32x32x16_bf16 v[18:33], v[210:213], v[10:13], v[18:33]
	ds_read_b128 v[6:9], v248 offset:13856
	s_waitcnt vmcnt(6)
	ds_write_b128 v251, v[194:197] offset:36864
	v_mfma_f32_32x32x16_bf16 v[34:49], v[214:217], v[10:13], v[34:49]
	s_waitcnt lgkmcnt(6)
	v_mfma_f32_32x32x16_bf16 v[114:129], v[228:231], v[14:17], v[114:129]
	ds_read_b128 v[210:213], v249 offset:64
	s_waitcnt lgkmcnt(6)
;     ...
;   for (int kt = 0; kt < nk; ++kt) {
;     __syncthreads();
;     if (kt + 1 < nk) {
;       u16* aw = As0 + ((kt + 1) & 1) * 256 * LD;
;       u16* bw = Bs0 + ((kt + 1) & 1) * 256 * LD;
; #pragma unroll
;       for (int i = 0; i < 4; ++i) { *(u32x4*)(aw + (srow + 64 * i) * LD + skc * 8) = ra[i]; *(u32x4*)(bw + (srow + 64 * i) * LD + skc * 8) = rb[i]; }
;     }
;     if (kt + 2 < nk) {
; #pragma unroll
;       for (int i = 0; i < 4; ++i) { ra[i] = *(const u32x4*)(Ag + (size_t)(64 * i) * K + (kt + 2) * 64); rb[i] = *(const u32x4*)(Bg[i] + (kt + 2) * 64); }
;     }
;     __builtin_amdgcn_sched_barrier(0);
;     const u16* as = As0 + (kt & 1) * 256 * LD + (wr * 128 + l31) * LD + h * 8;
;     const u16* bs = Bs0 + (kt & 1) * 256 * LD + (wc * 64 + l31) * LD + h * 8;
;     if (domma)
; #pragma unroll
;     for (int ks = 0; ks < 4; ++ks) {
;       bf16x8 wf[2], xf[4];
; #pragma unroll
;       for (int ct = 0; ct < 2; ++ct) wf[ct] = *(const bf16x8*)(bs + ct * 32 * LD + ks * 16);
; #pragma unroll
;       for (int tt = 0; tt < 4; ++tt) xf[tt] = *(const bf16x8*)(as + tt * 32 * LD + ks * 16);
; #pragma unroll
;       for (int ct = 0; ct < 2; ++ct)
; #pragma unroll
;         for (int tt = 0; tt < 4; ++tt) acc[ct][tt] = __builtin_amdgcn_mfma_f32_32x32x16_bf16(wf[ct], xf[tt], acc[ct][tt], 0, 0, 0);
;     }
;     __builtin_amdgcn_sched_barrier(0);
;   }
	v_mfma_f32_32x32x16_bf16 v[130:145], v[232:235], v[14:17], v[130:145]
	ds_read_b128 v[10:13], v248 offset:64
	s_waitcnt vmcnt(5)
	ds_write_b128 v250, v[166:169] offset:46080
	s_waitcnt lgkmcnt(7)
	v_mfma_f32_32x32x16_bf16 v[82:97], v[228:231], v[236:239], v[82:97]
	ds_read_b128 v[214:217], v249 offset:4672
	v_mfma_f32_32x32x16_bf16 v[98:113], v[232:235], v[236:239], v[98:113]
	ds_read_b128 v[14:17], v248 offset:4672
	s_waitcnt lgkmcnt(7)
	v_mfma_f32_32x32x16_bf16 v[50:65], v[228:231], v[2:5], v[50:65]
	ds_read_b128 v[236:239], v248 offset:9280
	s_waitcnt vmcnt(4)
	ds_write_b128 v251, v[198:201] offset:46080
	v_mfma_f32_32x32x16_bf16 v[66:81], v[232:235], v[2:5], v[66:81]
	s_waitcnt lgkmcnt(8)
	v_mfma_f32_32x32x16_bf16 v[18:33], v[228:231], v[6:9], v[18:33]
	ds_read_b128 v[2:5], v248 offset:13888
	v_mfma_f32_32x32x16_bf16 v[34:49], v[232:235], v[6:9], v[34:49]
	s_waitcnt vmcnt(3)
	ds_write_b128 v250, v[170:173] offset:55296
	s_waitcnt lgkmcnt(7)
	v_mfma_f32_32x32x16_bf16 v[114:129], v[210:213], v[10:13], v[114:129]
	ds_read_b128 v[228:231], v249 offset:96
	s_waitcnt lgkmcnt(6)
	v_mfma_f32_32x32x16_bf16 v[130:145], v[214:217], v[10:13], v[130:145]
	ds_read_b128 v[6:9], v248 offset:96
	s_waitcnt lgkmcnt(6)
	v_mfma_f32_32x32x16_bf16 v[82:97], v[210:213], v[14:17], v[82:97]
	ds_read_b128 v[232:235], v249 offset:4704
	s_waitcnt vmcnt(2)
	ds_write_b128 v251, v[202:205] offset:55296
	v_mfma_f32_32x32x16_bf16 v[98:113], v[214:217], v[14:17], v[98:113]
	ds_read_b128 v[10:13], v248 offset:4704
	s_waitcnt lgkmcnt(8)
	v_mfma_f32_32x32x16_bf16 v[50:65], v[210:213], v[236:239], v[50:65]
	ds_read_b128 v[14:17], v248 offset:9312
	v_mfma_f32_32x32x16_bf16 v[66:81], v[214:217], v[236:239], v[66:81]
	s_waitcnt vmcnt(1)
	ds_write_b128 v250, v[174:177] offset:64512
	s_waitcnt lgkmcnt(8)
	v_mfma_f32_32x32x16_bf16 v[18:33], v[210:213], v[2:5], v[18:33]
	ds_read_b128 v[236:239], v248 offset:13920
	v_mfma_f32_32x32x16_bf16 v[34:49], v[214:217], v[2:5], v[34:49]
	s_waitcnt lgkmcnt(6)
	v_mfma_f32_32x32x16_bf16 v[114:129], v[228:231], v[6:9], v[114:129]
	s_waitcnt vmcnt(0)
	ds_write_b128 v251, v[206:209] offset:64512
	s_waitcnt lgkmcnt(6)
	v_mfma_f32_32x32x16_bf16 v[130:145], v[232:235], v[6:9], v[130:145]
	s_waitcnt lgkmcnt(4)
	v_mfma_f32_32x32x16_bf16 v[82:97], v[228:231], v[10:13], v[82:97]
	v_mfma_f32_32x32x16_bf16 v[98:113], v[232:235], v[10:13], v[98:113]
	s_waitcnt lgkmcnt(3)
	v_mfma_f32_32x32x16_bf16 v[50:65], v[228:231], v[14:17], v[50:65]
	v_mfma_f32_32x32x16_bf16 v[66:81], v[232:235], v[14:17], v[66:81]
	s_waitcnt lgkmcnt(1)
	v_mfma_f32_32x32x16_bf16 v[18:33], v[228:231], v[236:239], v[18:33]
	v_mfma_f32_32x32x16_bf16 v[34:49], v[232:235], v[236:239], v[34:49]
	s_waitcnt lgkmcnt(0)
	s_barrier
	ds_read_b128 v[210:213], v249 offset:36864
	ds_read_b128 v[236:239], v248 offset:36864
	ds_read_b128 v[214:217], v249 offset:41472
	ds_read_b128 v[2:5], v248 offset:41472
	ds_read_b128 v[6:9], v248 offset:46080
	ds_read_b128 v[10:13], v248 offset:50688
	s_waitcnt lgkmcnt(4)
	v_mfma_f32_32x32x16_bf16 v[114:129], v[210:213], v[236:239], v[114:129]
	ds_read_b128 v[228:231], v249 offset:36896
	s_waitcnt lgkmcnt(4)
	v_mfma_f32_32x32x16_bf16 v[130:145], v[214:217], v[236:239], v[130:145]
	ds_read_b128 v[14:17], v248 offset:36896
	s_waitcnt lgkmcnt(4)
	v_mfma_f32_32x32x16_bf16 v[82:97], v[210:213], v[2:5], v[82:97]
	ds_read_b128 v[232:235], v249 offset:41504
	v_mfma_f32_32x32x16_bf16 v[98:113], v[214:217], v[2:5], v[98:113]
	ds_read_b128 v[236:239], v248 offset:41504
	s_waitcnt lgkmcnt(5)
	v_mfma_f32_32x32x16_bf16 v[50:65], v[210:213], v[6:9], v[50:65]
	ds_read_b128 v[2:5], v248 offset:46112
	v_mfma_f32_32x32x16_bf16 v[66:81], v[214:217], v[6:9], v[66:81]
	s_waitcnt lgkmcnt(5)
	v_mfma_f32_32x32x16_bf16 v[18:33], v[210:213], v[10:13], v[18:33]
	ds_read_b128 v[6:9], v248 offset:50720
	v_mfma_f32_32x32x16_bf16 v[34:49], v[214:217], v[10:13], v[34:49]
	s_waitcnt lgkmcnt(4)
	v_mfma_f32_32x32x16_bf16 v[114:129], v[228:231], v[14:17], v[114:129]
	ds_read_b128 v[210:213], v249 offset:36928
	s_waitcnt lgkmcnt(4)
	v_mfma_f32_32x32x16_bf16 v[130:145], v[232:235], v[14:17], v[130:145]
	ds_read_b128 v[10:13], v248 offset:36928
	s_waitcnt lgkmcnt(4)
	v_mfma_f32_32x32x16_bf16 v[82:97], v[228:231], v[236:239], v[82:97]
	ds_read_b128 v[214:217], v249 offset:41536
	v_mfma_f32_32x32x16_bf16 v[98:113], v[232:235], v[236:239], v[98:113]
	ds_read_b128 v[14:17], v248 offset:41536
	s_waitcnt lgkmcnt(5)
	v_mfma_f32_32x32x16_bf16 v[50:65], v[228:231], v[2:5], v[50:65]
	ds_read_b128 v[236:239], v248 offset:46144
	v_mfma_f32_32x32x16_bf16 v[66:81], v[232:235], v[2:5], v[66:81]
	s_waitcnt lgkmcnt(5)
	v_mfma_f32_32x32x16_bf16 v[18:33], v[228:231], v[6:9], v[18:33]
	ds_read_b128 v[2:5], v248 offset:50752
	v_mfma_f32_32x32x16_bf16 v[34:49], v[232:235], v[6:9], v[34:49]
	s_waitcnt lgkmcnt(4)
	v_mfma_f32_32x32x16_bf16 v[114:129], v[210:213], v[10:13], v[114:129]
	ds_read_b128 v[228:231], v249 offset:36960
	s_waitcnt lgkmcnt(4)
	v_mfma_f32_32x32x16_bf16 v[130:145], v[214:217], v[10:13], v[130:145]
	ds_read_b128 v[6:9], v248 offset:36960
	s_waitcnt lgkmcnt(4)
	v_mfma_f32_32x32x16_bf16 v[82:97], v[210:213], v[14:17], v[82:97]
	ds_read_b128 v[232:235], v249 offset:41568
	v_mfma_f32_32x32x16_bf16 v[98:113], v[214:217], v[14:17], v[98:113]
	ds_read_b128 v[10:13], v248 offset:41568
	s_waitcnt lgkmcnt(5)
	v_mfma_f32_32x32x16_bf16 v[50:65], v[210:213], v[236:239], v[50:65]
	ds_read_b128 v[14:17], v248 offset:46176
	v_mfma_f32_32x32x16_bf16 v[66:81], v[214:217], v[236:239], v[66:81]
	s_waitcnt lgkmcnt(5)
	v_mfma_f32_32x32x16_bf16 v[18:33], v[210:213], v[2:5], v[18:33]
	ds_read_b128 v[236:239], v248 offset:50784
	v_mfma_f32_32x32x16_bf16 v[34:49], v[214:217], v[2:5], v[34:49]
	s_waitcnt lgkmcnt(4)
;     ...
;   for (int kt = 0; kt < nk; ++kt) {
;     __syncthreads();
;     if (kt + 1 < nk) {
;       u16* aw = As0 + ((kt + 1) & 1) * 256 * LD;
;       u16* bw = Bs0 + ((kt + 1) & 1) * 256 * LD;
; #pragma unroll
;       for (int i = 0; i < 4; ++i) { *(u32x4*)(aw + (srow + 64 * i) * LD + skc * 8) = ra[i]; *(u32x4*)(bw + (srow + 64 * i) * LD + skc * 8) = rb[i]; }
;     }
;     if (kt + 2 < nk) {
; #pragma unroll
;       for (int i = 0; i < 4; ++i) { ra[i] = *(const u32x4*)(Ag + (size_t)(64 * i) * K + (kt + 2) * 64); rb[i] = *(const u32x4*)(Bg[i] + (kt + 2) * 64); }
;     }
;     __builtin_amdgcn_sched_barrier(0);
;     const u16* as = As0 + (kt & 1) * 256 * LD + (wr * 128 + l31) * LD + h * 8;
;     const u16* bs = Bs0 + (kt & 1) * 256 * LD + (wc * 64 + l31) * LD + h * 8;
;     if (domma)
; #pragma unroll
;     for (int ks = 0; ks < 4; ++ks) {
;       bf16x8 wf[2], xf[4];
; #pragma unroll
;       for (int ct = 0; ct < 2; ++ct) wf[ct] = *(const bf16x8*)(bs + ct * 32 * LD + ks * 16);
; #pragma unroll
;       for (int tt = 0; tt < 4; ++tt) xf[tt] = *(const bf16x8*)(as + tt * 32 * LD + ks * 16);
; #pragma unroll
;       for (int ct = 0; ct < 2; ++ct)
; #pragma unroll
;         for (int tt = 0; tt < 4; ++tt) acc[ct][tt] = __builtin_amdgcn_mfma_f32_32x32x16_bf16(wf[ct], xf[tt], acc[ct][tt], 0, 0, 0);
;     }
;     __builtin_amdgcn_sched_barrier(0);
;   }
;     ...
;   for (int Lx = jx; Lx < (NMT / 8) * NNT; Lx += nbx) {
;     const int grp = Lx / (2 * NNT), gi = Lx % (2 * NNT);
;     const int mt = xcd * (NMT / 8) + 2 * grp + (gi & 1), nt = gi >> 1;
	v_mfma_f32_32x32x16_bf16 v[114:129], v[228:231], v[6:9], v[114:129]
	s_waitcnt lgkmcnt(3)
	v_mfma_f32_32x32x16_bf16 v[130:145], v[232:235], v[6:9], v[130:145]
	s_waitcnt lgkmcnt(2)
	v_mfma_f32_32x32x16_bf16 v[82:97], v[228:231], v[10:13], v[82:97]
	v_mfma_f32_32x32x16_bf16 v[98:113], v[232:235], v[10:13], v[98:113]
	s_waitcnt lgkmcnt(1)
	v_mfma_f32_32x32x16_bf16 v[50:65], v[228:231], v[14:17], v[50:65]
	v_mfma_f32_32x32x16_bf16 v[66:81], v[232:235], v[14:17], v[66:81]
	s_waitcnt lgkmcnt(0)
	v_mfma_f32_32x32x16_bf16 v[18:33], v[228:231], v[236:239], v[18:33]
	v_mfma_f32_32x32x16_bf16 v[34:49], v[232:235], v[236:239], v[34:49]
	v_mov_b32_e32 v3, 0
	v_mov_b32_e32 v227, v223
	s_add_i32 s94, s58, s33
	s_min_i32 s94, s94, 0x10f
	s_mul_hi_i32 s6, s94, 0x78787879
	s_lshr_b32 s7, s6, 31
	s_ashr_i32 s6, s6, 4
	s_add_i32 s6, s6, s7
	s_mul_i32 s7, s6, 0xffffffde
	s_add_i32 s7, s94, s7
	s_lshl_b32 s6, s6, 1
	s_add_i32 s6, s6, s40
	s_and_b32 s31, s7, 1
	s_or_b32 s6, s6, s31
	s_lshr_b32 s7, s7, 1
	s_lshl_b32 s6, s6, 19
	s_lshl_b32 s7, s7, 19
	s_add_u32 s94, s16, s6
	s_addc_u32 s95, s17, 0
	s_add_u32 s96, s18, s7
	s_addc_u32 s97, s19, 0
	v_lshrrev_b32_e32 v229, 1, v223
	v_lshlrev_b32_e32 v229, 11, v229
	v_and_b32_e32 v230, 1, v223
	v_lshl_or_b32 v229, v230, 7, v229
	global_load_dword v230, v229, s[94:95]
	global_load_dword v231, v229, s[96:97]
	s_branch .LBB0_139
.Lp1_stage_only:
	v_lshrrev_b32_e32 v227, 3, v223
	v_lshlrev_b32_e32 v227, 11, v227
	v_lshlrev_b32_e32 v2, 4, v223
	v_and_b32_e32 v2, 0x70, v2
	v_or_b32_e32 v227, v227, v2
	s_lshl_b32 s6, s35, 11
	s_add_u32 s74, s16, s6
	s_addc_u32 s75, s17, 0
	s_add_u32 s76, s74, 0x20000
	s_addc_u32 s77, s75, 0
	s_add_u32 s78, s74, 0x40000
	s_addc_u32 s79, s75, 0
	s_add_u32 s80, s74, 0x60000
	s_addc_u32 s81, s75, 0
	s_lshl_b32 s6, s59, 11
	s_add_u32 s82, s18, s6
	s_addc_u32 s83, s19, 0
	s_add_u32 s84, s82, 0x20000
	s_addc_u32 s85, s83, 0
	s_add_u32 s86, s82, 0x40000
	s_addc_u32 s87, s83, 0
	s_add_u32 s92, s82, 0x60000
	s_addc_u32 s93, s83, 0
	global_load_dwordx4 v[146:149], v227, s[74:75] offset:256
	global_load_dwordx4 v[178:181], v227, s[82:83] offset:256
	global_load_dwordx4 v[150:153], v227, s[76:77] offset:256
	global_load_dwordx4 v[182:185], v227, s[84:85] offset:256
	global_load_dwordx4 v[154:157], v227, s[78:79] offset:256
	global_load_dwordx4 v[186:189], v227, s[86:87] offset:256
	global_load_dwordx4 v[158:161], v227, s[80:81] offset:256
	global_load_dwordx4 v[190:193], v227, s[92:93] offset:256
	global_load_dwordx4 v[162:165], v227, s[74:75] offset:384
	global_load_dwordx4 v[194:197], v227, s[82:83] offset:384
	global_load_dwordx4 v[166:169], v227, s[76:77] offset:384
	global_load_dwordx4 v[198:201], v227, s[84:85] offset:384
	global_load_dwordx4 v[170:173], v227, s[78:79] offset:384
	global_load_dwordx4 v[202:205], v227, s[86:87] offset:384
	global_load_dwordx4 v[174:177], v227, s[80:81] offset:384
	global_load_dwordx4 v[206:209], v227, s[92:93] offset:384
	s_waitcnt vmcnt(23)
	ds_write_b128 v251, v[36:39] offset:36864
	s_waitcnt vmcnt(22)
	ds_write_b128 v251, v[40:43] offset:46080
	s_waitcnt vmcnt(21)
	ds_write_b128 v251, v[44:47] offset:55296
	s_waitcnt vmcnt(20)
	ds_write_b128 v251, v[48:51] offset:64512
	s_waitcnt vmcnt(19)
	ds_write_b128 v250, v[52:55] offset:36864
	s_waitcnt vmcnt(18)
	ds_write_b128 v250, v[56:59] offset:46080
	s_waitcnt vmcnt(17)
	ds_write_b128 v250, v[60:63] offset:55296
	s_waitcnt vmcnt(16)
	ds_write_b128 v250, v[64:67] offset:64512
	s_waitcnt lgkmcnt(0)
	s_barrier
	s_waitcnt vmcnt(15)
	ds_write_b128 v250, v[146:149]
	global_load_dwordx4 v[146:149], v227, s[74:75] offset:512
	s_waitcnt vmcnt(15)
	ds_write_b128 v251, v[178:181]
	global_load_dwordx4 v[178:181], v227, s[82:83] offset:512
	s_waitcnt vmcnt(15)
	ds_write_b128 v250, v[150:153] offset:9216
	global_load_dwordx4 v[150:153], v227, s[76:77] offset:512
	s_waitcnt vmcnt(15)
	ds_write_b128 v251, v[182:185] offset:9216
	global_load_dwordx4 v[182:185], v227, s[84:85] offset:512
	s_waitcnt vmcnt(15)
	ds_write_b128 v250, v[154:157] offset:18432
	global_load_dwordx4 v[154:157], v227, s[78:79] offset:512
	s_waitcnt vmcnt(15)
	ds_write_b128 v251, v[186:189] offset:18432
	global_load_dwordx4 v[186:189], v227, s[86:87] offset:512
	s_waitcnt vmcnt(15)
	ds_write_b128 v250, v[158:161] offset:27648
	global_load_dwordx4 v[158:161], v227, s[80:81] offset:512
	s_waitcnt vmcnt(15)
	ds_write_b128 v251, v[190:193] offset:27648
	global_load_dwordx4 v[190:193], v227, s[92:93] offset:512
	s_waitcnt lgkmcnt(0)
	s_barrier
	s_waitcnt vmcnt(15)
	ds_write_b128 v250, v[162:165] offset:36864
	global_load_dwordx4 v[162:165], v227, s[74:75] offset:640
	s_waitcnt vmcnt(15)
	ds_write_b128 v251, v[194:197] offset:36864
	global_load_dwordx4 v[194:197], v227, s[82:83] offset:640
	s_waitcnt vmcnt(15)
	ds_write_b128 v250, v[166:169] offset:46080
	global_load_dwordx4 v[166:169], v227, s[76:77] offset:640
	s_waitcnt vmcnt(15)
	ds_write_b128 v251, v[198:201] offset:46080
	global_load_dwordx4 v[198:201], v227, s[84:85] offset:640
	s_waitcnt vmcnt(15)
	ds_write_b128 v250, v[170:173] offset:55296
	global_load_dwordx4 v[170:173], v227, s[78:79] offset:640
	s_waitcnt vmcnt(15)
	ds_write_b128 v251, v[202:205] offset:55296
	global_load_dwordx4 v[202:205], v227, s[86:87] offset:640
	s_waitcnt vmcnt(15)
	ds_write_b128 v250, v[174:177] offset:64512
	global_load_dwordx4 v[174:177], v227, s[80:81] offset:640
	s_waitcnt vmcnt(15)
	ds_write_b128 v251, v[206:209] offset:64512
	global_load_dwordx4 v[206:209], v227, s[92:93] offset:640
	s_waitcnt lgkmcnt(0)
	s_barrier
;     ...
;   for (int kt = 0; kt < nk; ++kt) {
;     __syncthreads();
;     if (kt + 1 < nk) {
;       u16* aw = As0 + ((kt + 1) & 1) * 256 * LD;
;       u16* bw = Bs0 + ((kt + 1) & 1) * 256 * LD;
; #pragma unroll
;       for (int i = 0; i < 4; ++i) { *(u32x4*)(aw + (srow + 64 * i) * LD + skc * 8) = ra[i]; *(u32x4*)(bw + (srow + 64 * i) * LD + skc * 8) = rb[i]; }
;     }
;     if (kt + 2 < nk) {
; #pragma unroll
;       for (int i = 0; i < 4; ++i) { ra[i] = *(const u32x4*)(Ag + (size_t)(64 * i) * K + (kt + 2) * 64); rb[i] = *(const u32x4*)(Bg[i] + (kt + 2) * 64); }
;     }
	s_waitcnt vmcnt(15)
	ds_write_b128 v250, v[146:149]
	global_load_dwordx4 v[146:149], v227, s[74:75] offset:768
	s_waitcnt vmcnt(15)
	ds_write_b128 v251, v[178:181]
	global_load_dwordx4 v[178:181], v227, s[82:83] offset:768
	s_waitcnt vmcnt(15)
	ds_write_b128 v250, v[150:153] offset:9216
	global_load_dwordx4 v[150:153], v227, s[76:77] offset:768
	s_waitcnt vmcnt(15)
	ds_write_b128 v251, v[182:185] offset:9216
	global_load_dwordx4 v[182:185], v227, s[84:85] offset:768
	s_waitcnt vmcnt(15)
	ds_write_b128 v250, v[154:157] offset:18432
	global_load_dwordx4 v[154:157], v227, s[78:79] offset:768
	s_waitcnt vmcnt(15)
	ds_write_b128 v251, v[186:189] offset:18432
	global_load_dwordx4 v[186:189], v227, s[86:87] offset:768
	s_waitcnt vmcnt(15)
	ds_write_b128 v250, v[158:161] offset:27648
	global_load_dwordx4 v[158:161], v227, s[80:81] offset:768
	s_waitcnt vmcnt(15)
	ds_write_b128 v251, v[190:193] offset:27648
	global_load_dwordx4 v[190:193], v227, s[92:93] offset:768
	s_waitcnt lgkmcnt(0)
	s_barrier
	s_waitcnt vmcnt(15)
	ds_write_b128 v250, v[162:165] offset:36864
	global_load_dwordx4 v[162:165], v227, s[74:75] offset:896
	s_waitcnt vmcnt(15)
	ds_write_b128 v251, v[194:197] offset:36864
	global_load_dwordx4 v[194:197], v227, s[82:83] offset:896
	s_waitcnt vmcnt(15)
	ds_write_b128 v250, v[166:169] offset:46080
	global_load_dwordx4 v[166:169], v227, s[76:77] offset:896
	s_waitcnt vmcnt(15)
	ds_write_b128 v251, v[198:201] offset:46080
	global_load_dwordx4 v[198:201], v227, s[84:85] offset:896
	s_waitcnt vmcnt(15)
	ds_write_b128 v250, v[170:173] offset:55296
	global_load_dwordx4 v[170:173], v227, s[78:79] offset:896
	s_waitcnt vmcnt(15)
	ds_write_b128 v251, v[202:205] offset:55296
	global_load_dwordx4 v[202:205], v227, s[86:87] offset:896
	s_waitcnt vmcnt(15)
	ds_write_b128 v250, v[174:177] offset:64512
	global_load_dwordx4 v[174:177], v227, s[80:81] offset:896
	s_waitcnt vmcnt(15)
	ds_write_b128 v251, v[206:209] offset:64512
	global_load_dwordx4 v[206:209], v227, s[92:93] offset:896
	s_waitcnt lgkmcnt(0)
	s_barrier
	s_waitcnt vmcnt(15)
	ds_write_b128 v250, v[146:149]
	global_load_dwordx4 v[146:149], v227, s[74:75] offset:1024
	s_waitcnt vmcnt(15)
	ds_write_b128 v251, v[178:181]
	global_load_dwordx4 v[178:181], v227, s[82:83] offset:1024
	s_waitcnt vmcnt(15)
	ds_write_b128 v250, v[150:153] offset:9216
	global_load_dwordx4 v[150:153], v227, s[76:77] offset:1024
	s_waitcnt vmcnt(15)
	ds_write_b128 v251, v[182:185] offset:9216
	global_load_dwordx4 v[182:185], v227, s[84:85] offset:1024
	s_waitcnt vmcnt(15)
	ds_write_b128 v250, v[154:157] offset:18432
	global_load_dwordx4 v[154:157], v227, s[78:79] offset:1024
	s_waitcnt vmcnt(15)
	ds_write_b128 v251, v[186:189] offset:18432
	global_load_dwordx4 v[186:189], v227, s[86:87] offset:1024
	s_waitcnt vmcnt(15)
	ds_write_b128 v250, v[158:161] offset:27648
	global_load_dwordx4 v[158:161], v227, s[80:81] offset:1024
	s_waitcnt vmcnt(15)
	ds_write_b128 v251, v[190:193] offset:27648
	global_load_dwordx4 v[190:193], v227, s[92:93] offset:1024
	s_waitcnt lgkmcnt(0)
	s_barrier
	s_waitcnt vmcnt(15)
	ds_write_b128 v250, v[162:165] offset:36864
	global_load_dwordx4 v[162:165], v227, s[74:75] offset:1152
	s_waitcnt vmcnt(15)
	ds_write_b128 v251, v[194:197] offset:36864
	global_load_dwordx4 v[194:197], v227, s[82:83] offset:1152
	s_waitcnt vmcnt(15)
	ds_write_b128 v250, v[166:169] offset:46080
	global_load_dwordx4 v[166:169], v227, s[76:77] offset:1152
	s_waitcnt vmcnt(15)
	ds_write_b128 v251, v[198:201] offset:46080
	global_load_dwordx4 v[198:201], v227, s[84:85] offset:1152
	s_waitcnt vmcnt(15)
	ds_write_b128 v250, v[170:173] offset:55296
	global_load_dwordx4 v[170:173], v227, s[78:79] offset:1152
	s_waitcnt vmcnt(15)
	ds_write_b128 v251, v[202:205] offset:55296
	global_load_dwordx4 v[202:205], v227, s[86:87] offset:1152
	s_waitcnt vmcnt(15)
	ds_write_b128 v250, v[174:177] offset:64512
	global_load_dwordx4 v[174:177], v227, s[80:81] offset:1152
	s_waitcnt vmcnt(15)
	ds_write_b128 v251, v[206:209] offset:64512
	global_load_dwordx4 v[206:209], v227, s[92:93] offset:1152
	s_waitcnt lgkmcnt(0)
	s_barrier
	s_waitcnt vmcnt(15)
	ds_write_b128 v250, v[146:149]
	global_load_dwordx4 v[146:149], v227, s[74:75] offset:1280
	s_waitcnt vmcnt(15)
	ds_write_b128 v251, v[178:181]
	global_load_dwordx4 v[178:181], v227, s[82:83] offset:1280
	s_waitcnt vmcnt(15)
	ds_write_b128 v250, v[150:153] offset:9216
	global_load_dwordx4 v[150:153], v227, s[76:77] offset:1280
	s_waitcnt vmcnt(15)
	ds_write_b128 v251, v[182:185] offset:9216
	global_load_dwordx4 v[182:185], v227, s[84:85] offset:1280
	s_waitcnt vmcnt(15)
	ds_write_b128 v250, v[154:157] offset:18432
	global_load_dwordx4 v[154:157], v227, s[78:79] offset:1280
	s_waitcnt vmcnt(15)
	ds_write_b128 v251, v[186:189] offset:18432
	global_load_dwordx4 v[186:189], v227, s[86:87] offset:1280
	s_waitcnt vmcnt(15)
	ds_write_b128 v250, v[158:161] offset:27648
	global_load_dwordx4 v[158:161], v227, s[80:81] offset:1280
	s_waitcnt vmcnt(15)
	ds_write_b128 v251, v[190:193] offset:27648
	global_load_dwordx4 v[190:193], v227, s[92:93] offset:1280
	s_waitcnt lgkmcnt(0)
	s_barrier
	s_waitcnt vmcnt(15)
	ds_write_b128 v250, v[162:165] offset:36864
	global_load_dwordx4 v[162:165], v227, s[74:75] offset:1408
	s_waitcnt vmcnt(15)
	ds_write_b128 v251, v[194:197] offset:36864
	global_load_dwordx4 v[194:197], v227, s[82:83] offset:1408
	s_waitcnt vmcnt(15)
	ds_write_b128 v250, v[166:169] offset:46080
	global_load_dwordx4 v[166:169], v227, s[76:77] offset:1408
	s_waitcnt vmcnt(15)
	ds_write_b128 v251, v[198:201] offset:46080
	global_load_dwordx4 v[198:201], v227, s[84:85] offset:1408
	s_waitcnt vmcnt(15)
	ds_write_b128 v250, v[170:173] offset:55296
	global_load_dwordx4 v[170:173], v227, s[78:79] offset:1408
	s_waitcnt vmcnt(15)
	ds_write_b128 v251, v[202:205] offset:55296
	global_load_dwordx4 v[202:205], v227, s[86:87] offset:1408
	s_waitcnt vmcnt(15)
	ds_write_b128 v250, v[174:177] offset:64512
	global_load_dwordx4 v[174:177], v227, s[80:81] offset:1408
	s_waitcnt vmcnt(15)
	ds_write_b128 v251, v[206:209] offset:64512
	global_load_dwordx4 v[206:209], v227, s[92:93] offset:1408
	s_waitcnt lgkmcnt(0)
	s_barrier
;     ...
;   for (int kt = 0; kt < nk; ++kt) {
;     __syncthreads();
;     if (kt + 1 < nk) {
;       u16* aw = As0 + ((kt + 1) & 1) * 256 * LD;
;       u16* bw = Bs0 + ((kt + 1) & 1) * 256 * LD;
; #pragma unroll
;       for (int i = 0; i < 4; ++i) { *(u32x4*)(aw + (srow + 64 * i) * LD + skc * 8) = ra[i]; *(u32x4*)(bw + (srow + 64 * i) * LD + skc * 8) = rb[i]; }
;     }
;     if (kt + 2 < nk) {
; #pragma unroll
;       for (int i = 0; i < 4; ++i) { ra[i] = *(const u32x4*)(Ag + (size_t)(64 * i) * K + (kt + 2) * 64); rb[i] = *(const u32x4*)(Bg[i] + (kt + 2) * 64); }
;     }
;     ...
;   for (int Lx = jx; Lx < (NMT / 8) * NNT; Lx += nbx) {
;     const int grp = Lx / (2 * NNT), gi = Lx % (2 * NNT);
;     const int mt = xcd * (NMT / 8) + 2 * grp + (gi & 1), nt = gi >> 1;
	s_waitcnt vmcnt(15)
	ds_write_b128 v250, v[146:149]
	global_load_dwordx4 v[146:149], v227, s[74:75] offset:1536
	s_waitcnt vmcnt(15)
	ds_write_b128 v251, v[178:181]
	global_load_dwordx4 v[178:181], v227, s[82:83] offset:1536
	s_waitcnt vmcnt(15)
	ds_write_b128 v250, v[150:153] offset:9216
	global_load_dwordx4 v[150:153], v227, s[76:77] offset:1536
	s_waitcnt vmcnt(15)
	ds_write_b128 v251, v[182:185] offset:9216
	global_load_dwordx4 v[182:185], v227, s[84:85] offset:1536
	s_waitcnt vmcnt(15)
	ds_write_b128 v250, v[154:157] offset:18432
	global_load_dwordx4 v[154:157], v227, s[78:79] offset:1536
	s_waitcnt vmcnt(15)
	ds_write_b128 v251, v[186:189] offset:18432
	global_load_dwordx4 v[186:189], v227, s[86:87] offset:1536
	s_waitcnt vmcnt(15)
	ds_write_b128 v250, v[158:161] offset:27648
	global_load_dwordx4 v[158:161], v227, s[80:81] offset:1536
	s_waitcnt vmcnt(15)
	ds_write_b128 v251, v[190:193] offset:27648
	global_load_dwordx4 v[190:193], v227, s[92:93] offset:1536
	s_waitcnt lgkmcnt(0)
	s_barrier
	s_waitcnt vmcnt(15)
	ds_write_b128 v250, v[162:165] offset:36864
	global_load_dwordx4 v[162:165], v227, s[74:75] offset:1664
	s_waitcnt vmcnt(15)
	ds_write_b128 v251, v[194:197] offset:36864
	global_load_dwordx4 v[194:197], v227, s[82:83] offset:1664
	s_waitcnt vmcnt(15)
	ds_write_b128 v250, v[166:169] offset:46080
	global_load_dwordx4 v[166:169], v227, s[76:77] offset:1664
	s_waitcnt vmcnt(15)
	ds_write_b128 v251, v[198:201] offset:46080
	global_load_dwordx4 v[198:201], v227, s[84:85] offset:1664
	s_waitcnt vmcnt(15)
	ds_write_b128 v250, v[170:173] offset:55296
	global_load_dwordx4 v[170:173], v227, s[78:79] offset:1664
	s_waitcnt vmcnt(15)
	ds_write_b128 v251, v[202:205] offset:55296
	global_load_dwordx4 v[202:205], v227, s[86:87] offset:1664
	s_waitcnt vmcnt(15)
	ds_write_b128 v250, v[174:177] offset:64512
	global_load_dwordx4 v[174:177], v227, s[80:81] offset:1664
	s_waitcnt vmcnt(15)
	ds_write_b128 v251, v[206:209] offset:64512
	global_load_dwordx4 v[206:209], v227, s[92:93] offset:1664
	s_waitcnt lgkmcnt(0)
	s_barrier
	s_waitcnt vmcnt(15)
	ds_write_b128 v250, v[146:149]
	global_load_dwordx4 v[146:149], v227, s[74:75] offset:1792
	s_waitcnt vmcnt(15)
	ds_write_b128 v251, v[178:181]
	global_load_dwordx4 v[178:181], v227, s[82:83] offset:1792
	s_waitcnt vmcnt(15)
	ds_write_b128 v250, v[150:153] offset:9216
	global_load_dwordx4 v[150:153], v227, s[76:77] offset:1792
	s_waitcnt vmcnt(15)
	ds_write_b128 v251, v[182:185] offset:9216
	global_load_dwordx4 v[182:185], v227, s[84:85] offset:1792
	s_waitcnt vmcnt(15)
	ds_write_b128 v250, v[154:157] offset:18432
	global_load_dwordx4 v[154:157], v227, s[78:79] offset:1792
	s_waitcnt vmcnt(15)
	ds_write_b128 v251, v[186:189] offset:18432
	global_load_dwordx4 v[186:189], v227, s[86:87] offset:1792
	s_waitcnt vmcnt(15)
	ds_write_b128 v250, v[158:161] offset:27648
	global_load_dwordx4 v[158:161], v227, s[80:81] offset:1792
	s_waitcnt vmcnt(15)
	ds_write_b128 v251, v[190:193] offset:27648
	global_load_dwordx4 v[190:193], v227, s[92:93] offset:1792
	s_waitcnt lgkmcnt(0)
	s_barrier
	s_waitcnt vmcnt(15)
	ds_write_b128 v250, v[162:165] offset:36864
	global_load_dwordx4 v[162:165], v227, s[74:75] offset:1920
	s_waitcnt vmcnt(15)
	ds_write_b128 v251, v[194:197] offset:36864
	global_load_dwordx4 v[194:197], v227, s[82:83] offset:1920
	s_waitcnt vmcnt(15)
	ds_write_b128 v250, v[166:169] offset:46080
	global_load_dwordx4 v[166:169], v227, s[76:77] offset:1920
	s_waitcnt vmcnt(15)
	ds_write_b128 v251, v[198:201] offset:46080
	global_load_dwordx4 v[198:201], v227, s[84:85] offset:1920
	s_waitcnt vmcnt(15)
	ds_write_b128 v250, v[170:173] offset:55296
	global_load_dwordx4 v[170:173], v227, s[78:79] offset:1920
	s_waitcnt vmcnt(15)
	ds_write_b128 v251, v[202:205] offset:55296
	global_load_dwordx4 v[202:205], v227, s[86:87] offset:1920
	s_waitcnt vmcnt(15)
	ds_write_b128 v250, v[174:177] offset:64512
	global_load_dwordx4 v[174:177], v227, s[80:81] offset:1920
	s_waitcnt vmcnt(15)
	ds_write_b128 v251, v[206:209] offset:64512
	global_load_dwordx4 v[206:209], v227, s[92:93] offset:1920
	s_waitcnt lgkmcnt(0)
	s_barrier
	s_waitcnt vmcnt(15)
	ds_write_b128 v250, v[146:149]
	s_waitcnt vmcnt(14)
	ds_write_b128 v251, v[178:181]
	s_waitcnt vmcnt(13)
	ds_write_b128 v250, v[150:153] offset:9216
	s_waitcnt vmcnt(12)
	ds_write_b128 v251, v[182:185] offset:9216
	s_waitcnt vmcnt(11)
	ds_write_b128 v250, v[154:157] offset:18432
	s_waitcnt vmcnt(10)
	ds_write_b128 v251, v[186:189] offset:18432
	s_waitcnt vmcnt(9)
	ds_write_b128 v250, v[158:161] offset:27648
	s_waitcnt vmcnt(8)
	ds_write_b128 v251, v[190:193] offset:27648
	s_waitcnt lgkmcnt(0)
	s_barrier
	s_waitcnt vmcnt(7)
	ds_write_b128 v250, v[162:165] offset:36864
	s_waitcnt vmcnt(6)
	ds_write_b128 v251, v[194:197] offset:36864
	s_waitcnt vmcnt(5)
	ds_write_b128 v250, v[166:169] offset:46080
	s_waitcnt vmcnt(4)
	ds_write_b128 v251, v[198:201] offset:46080
	s_waitcnt vmcnt(3)
	ds_write_b128 v250, v[170:173] offset:55296
	s_waitcnt vmcnt(2)
	ds_write_b128 v251, v[202:205] offset:55296
	s_waitcnt vmcnt(1)
	ds_write_b128 v250, v[174:177] offset:64512
	s_waitcnt vmcnt(0)
	ds_write_b128 v251, v[206:209] offset:64512
	s_waitcnt lgkmcnt(0)
	s_barrier
	v_mov_b32_e32 v3, 0
	v_mov_b32_e32 v227, v223
	s_add_i32 s94, s58, s33
	s_min_i32 s94, s94, 0x10f
	s_mul_hi_i32 s6, s94, 0x78787879
	s_lshr_b32 s7, s6, 31
	s_ashr_i32 s6, s6, 4
	s_add_i32 s6, s6, s7
	s_mul_i32 s7, s6, 0xffffffde
	s_add_i32 s7, s94, s7
	s_lshl_b32 s6, s6, 1
	s_add_i32 s6, s6, s40
	s_and_b32 s31, s7, 1
	s_or_b32 s6, s6, s31
	s_lshr_b32 s7, s7, 1
	s_lshl_b32 s6, s6, 19
	s_lshl_b32 s7, s7, 19
	s_add_u32 s94, s16, s6
	s_addc_u32 s95, s17, 0
	s_add_u32 s96, s18, s7
	s_addc_u32 s97, s19, 0
	v_lshrrev_b32_e32 v229, 1, v223
	v_lshlrev_b32_e32 v229, 11, v229
	v_and_b32_e32 v230, 1, v223
	v_lshl_or_b32 v229, v230, 7, v229
	global_load_dword v230, v229, s[94:95]
	global_load_dword v231, v229, s[96:97]
	s_branch .LBB0_139

; __global__ void __launch_bounds__(NT) fwd_mega(Params p) {
	.amdhsa_kernel _Z8fwd_mega6Params
		.amdhsa_group_segment_fixed_size 0
		.amdhsa_private_segment_fixed_size 0
		.amdhsa_kernarg_size 592
		.amdhsa_user_sgpr_count 2
		.amdhsa_user_sgpr_dispatch_ptr 0
		.amdhsa_user_sgpr_queue_ptr 0
		.amdhsa_user_sgpr_kernarg_segment_ptr 1
		.amdhsa_user_sgpr_dispatch_id 0
		.amdhsa_user_sgpr_kernarg_preload_length 0
		.amdhsa_user_sgpr_kernarg_preload_offset 0
		.amdhsa_user_sgpr_private_segment_size 0
		.amdhsa_uses_dynamic_stack 0
		.amdhsa_enable_private_segment 0
		.amdhsa_system_sgpr_workgroup_id_x 1
		.amdhsa_system_sgpr_workgroup_id_y 0
		.amdhsa_system_sgpr_workgroup_id_z 0
		.amdhsa_system_sgpr_workgroup_info 0
		.amdhsa_system_vgpr_workitem_id 2
		.amdhsa_next_free_vgpr 256
		.amdhsa_next_free_sgpr 98
		.amdhsa_accum_offset 256
		.amdhsa_reserve_vcc 1
		.amdhsa_float_round_mode_32 0
		.amdhsa_float_round_mode_16_64 0
		.amdhsa_float_denorm_mode_32 3
		.amdhsa_float_denorm_mode_16_64 3
		.amdhsa_dx10_clamp 1
		.amdhsa_ieee_mode 1
		.amdhsa_fp16_overflow 0
		.amdhsa_tg_split 0
		.amdhsa_exception_fp_ieee_invalid_op 0
		.amdhsa_exception_fp_denorm_src 0
		.amdhsa_exception_fp_ieee_div_zero 0
		.amdhsa_exception_fp_ieee_overflow 0
		.amdhsa_exception_fp_ieee_underflow 0
		.amdhsa_exception_fp_ieee_inexact 0
		.amdhsa_exception_int_div_zero 0
	.end_amdhsa_kernel

; __global__ void __launch_bounds__(NT) fwd_mega(Params p) {
amdhsa.kernels:
  - .agpr_count:     0
    .args:
      - .offset:         0
        .size:           336
        .value_kind:     by_value
      - .offset:         336
        .size:           4
        .value_kind:     hidden_block_count_x
      - .offset:         340
        .size:           4
        .value_kind:     hidden_block_count_y
      - .offset:         344
        .size:           4
        .value_kind:     hidden_block_count_z
      - .offset:         348
        .size:           2
        .value_kind:     hidden_group_size_x
      - .offset:         350
        .size:           2
        .value_kind:     hidden_group_size_y
      - .offset:         352
        .size:           2
        .value_kind:     hidden_group_size_z
      - .offset:         354
        .size:           2
        .value_kind:     hidden_remainder_x
      - .offset:         356
        .size:           2
        .value_kind:     hidden_remainder_y
      - .offset:         358
        .size:           2
        .value_kind:     hidden_remainder_z
      - .offset:         376
        .size:           8
        .value_kind:     hidden_global_offset_x
      - .offset:         384
        .size:           8
        .value_kind:     hidden_global_offset_y
      - .offset:         392
        .size:           8
        .value_kind:     hidden_global_offset_z
      - .offset:         400
        .size:           2
        .value_kind:     hidden_grid_dims
      - .offset:         424
        .size:           8
        .value_kind:     hidden_multigrid_sync_arg
      - .offset:         456
        .size:           4
        .value_kind:     hidden_dynamic_lds_size
    .group_segment_fixed_size: 0
    .kernarg_segment_align: 8
    .kernarg_segment_size: 592
    .language:       OpenCL C
    .language_version:
      - 2
      - 0
    .max_flat_workgroup_size: 512
    .name:           _Z8fwd_mega6Params
    .private_segment_fixed_size: 0
    .sgpr_count:     104
    .sgpr_spill_count: 0
    .symbol:         _Z8fwd_mega6Params.kd
    .uniform_work_group_size: 1
    .uses_dynamic_stack: false
    .vgpr_count:     256
    .vgpr_spill_count: 0
    .wavefront_size: 64
